# batched residual/gate loads in out-proj and FFN-out epilogues; RWKV scan chunk body hand-scheduled (state update U-S split, type-clustered issue order)
# speedup vs baseline: 1.0204x; 1.0204x over previous
.LBB0_53:
	s_mul_i32 s10, s9, 0x5000
	v_add_u32_e32 v156, s10, v142
	v_lshl_add_u64 v[126:127], v[124:125], 0, s[0:1]
	v_readfirstlane_b32 s10, v156
	v_add_u32_e32 v136, 0x1000, v156
	v_lshl_add_u64 v[134:135], v[126:127], 0, s[2:3]
	s_mov_b32 m0, s10
	v_lshl_add_u64 v[138:139], v[122:123], 0, s[0:1]
	v_readfirstlane_b32 s10, v136
	s_waitcnt vmcnt(5)
	s_barrier
	global_load_lds_dwordx4 v[134:135], off
	v_lshl_add_u64 v[134:135], v[138:139], 0, s[2:3]
	s_mov_b32 m0, s10
	v_add_u32_e32 v140, 0x2000, v156
	global_load_lds_dwordx4 v[134:135], off
	v_lshl_add_u64 v[134:135], v[120:121], 0, s[0:1]
	v_readfirstlane_b32 s10, v140
	v_lshl_add_u64 v[136:137], v[134:135], 0, s[2:3]
	s_mov_b32 m0, s10
	v_add_u32_e32 v154, 0x3000, v156
	global_load_lds_dwordx4 v[136:137], off
	v_lshl_add_u64 v[136:137], v[118:119], 0, s[0:1]
	v_readfirstlane_b32 s10, v154
	v_lshl_add_u64 v[140:141], v[136:137], 0, s[2:3]
	s_mov_b32 m0, s10
	v_add_u32_e32 v156, 0x4000, v156
	global_load_lds_dwordx4 v[140:141], off
	v_lshl_add_u64 v[140:141], v[116:117], 0, s[0:1]
	v_readfirstlane_b32 s10, v156
	v_lshl_add_u64 v[154:155], v[140:141], 0, s[2:3]
	s_mov_b32 m0, s10
	s_mul_i32 s10, s8, 0x5000
	global_load_lds_dwordx4 v[154:155], off
	v_or_b32_e32 v154, s10, v147
	v_add_u32_e32 v170, v154, v128
	ds_read_b128 v[154:157], v170
	ds_read_b128 v[158:161], v170 offset:1024
	ds_read_b128 v[162:165], v170 offset:2048
	ds_read_b128 v[166:169], v170 offset:3072
	ds_read_b128 v[200:203], v170 offset:4096
	ds_read_b128 v[204:207], v170 offset:5120
	v_or_b32_e32 v170, s10, v149
	v_add_u32_e32 v170, v170, v148
	s_add_i32 s8, s8, 1
	s_add_i32 s9, s9, 1
	ds_read_b128 v[208:211], v170 offset:12288
	ds_read_b128 v[212:215], v170 offset:13312
	ds_read_b128 v[216:219], v170 offset:14336
	ds_read_b128 v[220:223], v170 offset:15360
	s_cmp_lg_u32 s8, 3
	s_cselect_b32 s8, s8, 0
	s_cmp_lg_u32 s9, 3
	s_cselect_b32 s9, s9, 0
	s_mul_i32 s10, s9, 0x5000
	s_waitcnt lgkmcnt(0)
	v_mfma_f32_16x16x32_bf16 v[92:95], v[208:211], v[154:157], v[92:95]
	v_lshl_add_u64 v[126:127], v[126:127], 0, s[30:31]
	s_waitcnt vmcnt(5)
	s_barrier
	v_mfma_f32_16x16x32_bf16 v[88:91], v[212:215], v[154:157], v[88:91]
	s_add_i32 s9, s9, 1
	v_mfma_f32_16x16x32_bf16 v[84:87], v[216:219], v[154:157], v[84:87]
	v_mfma_f32_16x16x32_bf16 v[80:83], v[220:223], v[154:157], v[80:83]
	v_add_u32_e32 v154, s10, v142
	s_nop 0
	v_readfirstlane_b32 s10, v154
	s_mov_b32 m0, s10
	v_mfma_f32_16x16x32_bf16 v[76:79], v[208:211], v[158:161], v[76:79]
	global_load_lds_dwordx4 v[126:127], off
	v_lshl_add_u64 v[126:127], v[138:139], 0, s[30:31]
	v_add_u32_e32 v138, 0x1000, v154
	v_mfma_f32_16x16x32_bf16 v[72:75], v[212:215], v[158:161], v[72:75]
	v_readfirstlane_b32 s10, v138
	s_mov_b32 m0, s10
	s_nop 0
	global_load_lds_dwordx4 v[126:127], off
	v_lshl_add_u64 v[126:127], v[134:135], 0, s[30:31]
	v_add_u32_e32 v134, 0x2000, v154
	v_mfma_f32_16x16x32_bf16 v[68:71], v[216:219], v[158:161], v[68:71]
	v_readfirstlane_b32 s10, v134
	v_add_u32_e32 v134, 0x3000, v154
	s_mov_b32 m0, s10
	v_readfirstlane_b32 s10, v134
	v_add_u32_e32 v134, 0x4000, v154
	global_load_lds_dwordx4 v[126:127], off
	v_lshl_add_u64 v[126:127], v[136:137], 0, s[30:31]
	s_mov_b32 m0, s10
	v_readfirstlane_b32 s10, v134
	global_load_lds_dwordx4 v[126:127], off
	v_lshl_add_u64 v[126:127], v[140:141], 0, s[30:31]
	s_mov_b32 m0, s10
	s_mul_i32 s10, s8, 0x5000
	global_load_lds_dwordx4 v[126:127], off
	v_or_b32_e32 v126, s10, v147
	v_add_u32_e32 v126, v126, v128
	v_mfma_f32_16x16x32_bf16 v[64:67], v[220:223], v[158:161], v[64:67]
	s_add_i32 s8, s8, 1
	s_cmp_lg_u32 s8, 3
	s_cselect_b32 s8, s8, 0
	v_mfma_f32_16x16x32_bf16 v[60:63], v[208:211], v[162:165], v[60:63]
	s_cmp_lg_u32 s9, 3
	s_cselect_b32 s9, s9, 0
	s_add_u32 s0, s0, 0x80
	v_mfma_f32_16x16x32_bf16 v[56:59], v[212:215], v[162:165], v[56:59]
	s_addc_u32 s1, s1, 0
	s_cmpk_eq_i32 s0, 0x1580
	v_mfma_f32_16x16x32_bf16 v[52:55], v[216:219], v[162:165], v[52:55]
	v_mfma_f32_16x16x32_bf16 v[48:51], v[220:223], v[162:165], v[48:51]
	v_mfma_f32_16x16x32_bf16 v[44:47], v[208:211], v[166:169], v[44:47]
	v_mfma_f32_16x16x32_bf16 v[40:43], v[212:215], v[166:169], v[40:43]
	v_mfma_f32_16x16x32_bf16 v[36:39], v[216:219], v[166:169], v[36:39]
	v_mfma_f32_16x16x32_bf16 v[32:35], v[220:223], v[166:169], v[32:35]
	ds_read_b128 v[134:137], v126
	ds_read_b128 v[138:141], v126 offset:1024
	ds_read_b128 v[154:157], v126 offset:2048
	ds_read_b128 v[158:161], v126 offset:3072
	ds_read_b128 v[162:165], v126 offset:4096
	ds_read_b128 v[166:169], v126 offset:5120
	v_or_b32_e32 v126, s10, v149
	v_add_u32_e32 v126, v126, v148
	v_mfma_f32_16x16x32_bf16 v[28:31], v[208:211], v[200:203], v[28:31]
	v_mfma_f32_16x16x32_bf16 v[24:27], v[212:215], v[200:203], v[24:27]
	v_mfma_f32_16x16x32_bf16 v[20:23], v[216:219], v[200:203], v[20:23]
	v_mfma_f32_16x16x32_bf16 v[16:19], v[220:223], v[200:203], v[16:19]
	v_mfma_f32_16x16x32_bf16 v[8:11], v[208:211], v[204:207], v[8:11]
	v_mfma_f32_16x16x32_bf16 v[4:7], v[212:215], v[204:207], v[4:7]
	v_mfma_f32_16x16x32_bf16 v[12:15], v[216:219], v[204:207], v[12:15]
	v_mfma_f32_16x16x32_bf16 v[0:3], v[220:223], v[204:207], v[0:3]
	ds_read_b128 v[200:203], v126 offset:12288
	ds_read_b128 v[204:207], v126 offset:13312
	ds_read_b128 v[208:211], v126 offset:14336
	ds_read_b128 v[212:215], v126 offset:15360
	s_waitcnt lgkmcnt(0)
	v_mfma_f32_16x16x32_bf16 v[92:95], v[200:203], v[134:137], v[92:95]
	v_mfma_f32_16x16x32_bf16 v[88:91], v[204:207], v[134:137], v[88:91]
	v_mfma_f32_16x16x32_bf16 v[84:87], v[208:211], v[134:137], v[84:87]
	v_mfma_f32_16x16x32_bf16 v[80:83], v[212:215], v[134:137], v[80:83]
	v_mfma_f32_16x16x32_bf16 v[76:79], v[200:203], v[138:141], v[76:79]
	v_mfma_f32_16x16x32_bf16 v[72:75], v[204:207], v[138:141], v[72:75]
	v_mfma_f32_16x16x32_bf16 v[68:71], v[208:211], v[138:141], v[68:71]
	v_mfma_f32_16x16x32_bf16 v[64:67], v[212:215], v[138:141], v[64:67]
	v_mfma_f32_16x16x32_bf16 v[60:63], v[200:203], v[154:157], v[60:63]
	v_mfma_f32_16x16x32_bf16 v[56:59], v[204:207], v[154:157], v[56:59]
	v_mfma_f32_16x16x32_bf16 v[52:55], v[208:211], v[154:157], v[52:55]
	v_mfma_f32_16x16x32_bf16 v[48:51], v[212:215], v[154:157], v[48:51]
	v_mfma_f32_16x16x32_bf16 v[44:47], v[200:203], v[158:161], v[44:47]
	v_mfma_f32_16x16x32_bf16 v[40:43], v[204:207], v[158:161], v[40:43]
	v_mfma_f32_16x16x32_bf16 v[36:39], v[208:211], v[158:161], v[36:39]
	v_mfma_f32_16x16x32_bf16 v[32:35], v[212:215], v[158:161], v[32:35]
	v_mfma_f32_16x16x32_bf16 v[28:31], v[200:203], v[162:165], v[28:31]
	v_mfma_f32_16x16x32_bf16 v[24:27], v[204:207], v[162:165], v[24:27]
	v_mfma_f32_16x16x32_bf16 v[20:23], v[208:211], v[162:165], v[20:23]
	v_mfma_f32_16x16x32_bf16 v[16:19], v[212:215], v[162:165], v[16:19]
	v_mfma_f32_16x16x32_bf16 v[8:11], v[200:203], v[166:169], v[8:11]
	v_mfma_f32_16x16x32_bf16 v[4:7], v[204:207], v[166:169], v[4:7]
	v_mfma_f32_16x16x32_bf16 v[12:15], v[208:211], v[166:169], v[12:15]
	v_mfma_f32_16x16x32_bf16 v[0:3], v[212:215], v[166:169], v[0:3]
	s_cbranch_scc0 .LBB0_53
	v_add_u32_e32 v170, v147, v128
	v_add_u32_e32 v172, v149, v148
	s_waitcnt vmcnt(5)
	s_barrier
	ds_read_b128 v[116:119], v170 offset:40960
	ds_read_b128 v[120:123], v170 offset:41984
	ds_read_b128 v[124:127], v170 offset:43008
	ds_read_b128 v[134:137], v170 offset:44032
	ds_read_b128 v[138:141], v170 offset:45056
	ds_read_b128 v[154:157], v170 offset:46080
	ds_read_b128 v[158:161], v172 offset:53248
	ds_read_b128 v[162:165], v172 offset:54272
	ds_read_b128 v[166:169], v172 offset:55296
	ds_read_b128 v[200:203], v172 offset:56320
	s_waitcnt lgkmcnt(0)
	v_mfma_f32_16x16x32_bf16 v[92:95], v[158:161], v[116:119], v[92:95]
	s_waitcnt vmcnt(0)
	s_barrier
	s_mulk_i32 s7, 0xc0
	v_mfma_f32_16x16x32_bf16 v[88:91], v[162:165], v[116:119], v[88:91]
	v_readlane_b32 s8, v243, 5
	v_readlane_b32 s14, v243, 11
	v_readlane_b32 s15, v243, 12
	v_mfma_f32_16x16x32_bf16 v[84:87], v[166:169], v[116:119], v[84:87]
	v_readlane_b32 s9, v243, 6
	v_readlane_b32 s10, v243, 7
	v_readlane_b32 s11, v243, 8
	v_mfma_f32_16x16x32_bf16 v[80:83], v[200:203], v[116:119], v[80:83]
	v_readlane_b32 s12, v243, 9
	v_readlane_b32 s13, v243, 10
	v_readlane_b32 s16, v243, 13
	v_mfma_f32_16x16x32_bf16 v[76:79], v[158:161], v[120:123], v[76:79]
	v_readlane_b32 s17, v243, 14
	v_readlane_b32 s18, v243, 15
	v_readlane_b32 s19, v243, 16
	v_mfma_f32_16x16x32_bf16 v[72:75], v[162:165], v[120:123], v[72:75]
	v_readlane_b32 s20, v243, 17
	v_readlane_b32 s21, v243, 18
	v_readlane_b32 s22, v243, 19
	v_mfma_f32_16x16x32_bf16 v[68:71], v[166:169], v[120:123], v[68:71]
	v_readlane_b32 s23, v243, 20
	s_mov_b64 s[24:25], 0x5000
	s_add_i32 s5, s5, s51
	v_mfma_f32_16x16x32_bf16 v[64:67], v[200:203], v[120:123], v[64:67]
	s_cmpk_gt_i32 s5, 0xff
	v_mfma_f32_16x16x32_bf16 v[60:63], v[158:161], v[124:127], v[60:63]
	v_mfma_f32_16x16x32_bf16 v[56:59], v[162:165], v[124:127], v[56:59]
	v_mfma_f32_16x16x32_bf16 v[52:55], v[166:169], v[124:127], v[52:55]
	v_mfma_f32_16x16x32_bf16 v[48:51], v[200:203], v[124:127], v[48:51]
	v_mfma_f32_16x16x32_bf16 v[44:47], v[158:161], v[134:137], v[44:47]
	v_mfma_f32_16x16x32_bf16 v[40:43], v[162:165], v[134:137], v[40:43]
	v_mfma_f32_16x16x32_bf16 v[36:39], v[166:169], v[134:137], v[36:39]
	v_mfma_f32_16x16x32_bf16 v[32:35], v[200:203], v[134:137], v[32:35]
	v_mfma_f32_16x16x32_bf16 v[28:31], v[158:161], v[138:141], v[28:31]
	v_mfma_f32_16x16x32_bf16 v[24:27], v[162:165], v[138:141], v[24:27]
	v_mfma_f32_16x16x32_bf16 v[20:23], v[166:169], v[138:141], v[20:23]
	v_mfma_f32_16x16x32_bf16 v[16:19], v[200:203], v[138:141], v[16:19]
	v_mfma_f32_16x16x32_bf16 v[8:11], v[158:161], v[154:157], v[8:11]
	v_mfma_f32_16x16x32_bf16 v[4:7], v[162:165], v[154:157], v[4:7]
	v_mfma_f32_16x16x32_bf16 v[116:119], v[166:169], v[154:157], v[12:15]
	v_mfma_f32_16x16x32_bf16 v[0:3], v[200:203], v[154:157], v[0:3]
	s_nop 1
	ds_read_b128 v[12:15], v170
	ds_read_b128 v[120:123], v170 offset:1024
	ds_read_b128 v[124:127], v170 offset:2048
	ds_read_b128 v[134:137], v170 offset:3072
	ds_read_b128 v[138:141], v170 offset:4096
	ds_read_b128 v[154:157], v170 offset:5120
	ds_read_b128 v[158:161], v172 offset:12288
	ds_read_b128 v[162:165], v172 offset:13312
	ds_read_b128 v[166:169], v172 offset:14336
	ds_read_b128 v[200:203], v172 offset:15360
	s_waitcnt lgkmcnt(0)
	v_mfma_f32_16x16x32_bf16 v[76:79], v[158:161], v[120:123], v[76:79]
	v_mfma_f32_16x16x32_bf16 v[72:75], v[162:165], v[120:123], v[72:75]
	v_mfma_f32_16x16x32_bf16 v[68:71], v[166:169], v[120:123], v[68:71]
	v_mfma_f32_16x16x32_bf16 v[64:67], v[200:203], v[120:123], v[64:67]
	v_mfma_f32_16x16x32_bf16 v[204:207], v[158:161], v[12:15], v[92:95]
	v_mfma_f32_16x16x32_bf16 v[88:91], v[162:165], v[12:15], v[88:91]
	v_mfma_f32_16x16x32_bf16 v[84:87], v[166:169], v[12:15], v[84:87]
	v_mfma_f32_16x16x32_bf16 v[80:83], v[200:203], v[12:15], v[80:83]
	v_mfma_f32_16x16x32_bf16 v[12:15], v[158:161], v[154:157], v[8:11]
	v_mfma_f32_16x16x32_bf16 v[8:11], v[162:165], v[154:157], v[4:7]
	v_mfma_f32_16x16x32_bf16 v[4:7], v[166:169], v[154:157], v[116:119]
	v_mfma_f32_16x16x32_bf16 v[28:31], v[158:161], v[138:141], v[28:31]
	v_mfma_f32_16x16x32_bf16 v[24:27], v[162:165], v[138:141], v[24:27]
	v_mfma_f32_16x16x32_bf16 v[20:23], v[166:169], v[138:141], v[20:23]
	v_mfma_f32_16x16x32_bf16 v[16:19], v[200:203], v[138:141], v[16:19]
	v_mfma_f32_16x16x32_bf16 v[60:63], v[158:161], v[124:127], v[60:63]
	v_mfma_f32_16x16x32_bf16 v[56:59], v[162:165], v[124:127], v[56:59]
	v_mfma_f32_16x16x32_bf16 v[52:55], v[166:169], v[124:127], v[52:55]
	v_mfma_f32_16x16x32_bf16 v[48:51], v[200:203], v[124:127], v[48:51]
	v_mfma_f32_16x16x32_bf16 v[44:47], v[158:161], v[134:137], v[44:47]
	v_mfma_f32_16x16x32_bf16 v[40:43], v[162:165], v[134:137], v[40:43]
	v_mfma_f32_16x16x32_bf16 v[36:39], v[166:169], v[134:137], v[36:39]
	v_mfma_f32_16x16x32_bf16 v[32:35], v[200:203], v[134:137], v[32:35]
	v_mfma_f32_16x16x32_bf16 v[0:3], v[200:203], v[154:157], v[0:3]
	v_readlane_b32 s10, v242, 27
	v_readlane_b32 s11, v242, 28
	v_readlane_b32 s12, v242, 29
	v_readlane_b32 s13, v242, 30
	v_readlane_b32 s14, v243, 11
	v_readlane_b32 s15, v243, 12
	s_mov_b32 s8, 0x3fd744fd
	v_add_u32_e32 v236, s7, v145
	v_or_b32_e32 v254, s6, v146
	v_mov_b32_e32 v255, 0
	v_or_b32_e32 v237, v236, v133
	v_lshlrev_b64 v[254:255], 2, v[254:255]
	s_nop 0
	v_lshl_add_u64 v[248:249], s[10:11], 0, v[254:255]
	v_lshl_add_u64 v[250:251], s[12:13], 0, v[254:255]
	v_lshl_add_u64 v[252:253], s[14:15], 0, v[254:255]
	s_mov_b64 s[10:11], 0x5000
	v_mov_b32_e32 v255, 0
	v_lshl_add_u64 v[252:253], v[252:253], 0, s[10:11]
	v_add_u32_e32 v254, 0, v237
	v_add_u32_e32 v236, 0xfffff000, v254
	v_cmp_lt_i32_e32 vcc, 0xfff, v254
	v_lshrrev_b32_e32 v236, 10, v236
	v_lshlrev_b32_e32 v254, 12, v254
	v_add_u32_e32 v236, 1, v236
	v_cndmask_b32_e32 v236, 0, v236, vcc
	v_lshl_add_u64 v[224:225], v[254:255], 0, v[248:249]
	v_lshl_add_u64 v[228:229], v[254:255], 0, v[250:251]
	v_add_u32_e32 v236, s4, v236
	v_mad_i64_i32 v[232:233], s[0:1], v236, s33, v[252:253]
	v_add_u32_e32 v254, 16, v237
	v_add_u32_e32 v236, 0xfffff000, v254
	v_cmp_lt_i32_e32 vcc, 0xfff, v254
	v_lshrrev_b32_e32 v236, 10, v236
	v_lshlrev_b32_e32 v254, 12, v254
	v_add_u32_e32 v236, 1, v236
	v_cndmask_b32_e32 v236, 0, v236, vcc
	v_lshl_add_u64 v[226:227], v[254:255], 0, v[248:249]
	v_lshl_add_u64 v[230:231], v[254:255], 0, v[250:251]
	v_add_u32_e32 v236, s4, v236
	v_mad_i64_i32 v[234:235], s[0:1], v236, s33, v[252:253]
	global_load_dwordx4 v[154:157], v[224:225], off
	global_load_dwordx4 v[116:119], v[232:233], off
	global_load_dwordx4 v[158:161], v[224:225], off offset:64
	global_load_dwordx4 v[120:123], v[232:233], off offset:64
	global_load_dwordx4 v[162:165], v[224:225], off offset:128
	global_load_dwordx4 v[124:127], v[232:233], off offset:128
	global_load_dwordx4 v[166:169], v[224:225], off offset:192
	global_load_dwordx4 v[134:137], v[232:233], off offset:192
	global_load_dwordx4 v[208:211], v[226:227], off
	global_load_dwordx4 v[138:141], v[234:235], off
	global_load_dwordx4 v[212:215], v[226:227], off offset:64
	global_load_dwordx4 v[200:203], v[234:235], off offset:64
	global_load_dwordx4 v[216:219], v[226:227], off offset:128
	global_load_dwordx4 v[92:95], v[234:235], off offset:128
	global_load_dwordx4 v[220:223], v[226:227], off offset:192
	global_load_dwordx4 v[244:247], v[234:235], off offset:192
	s_waitcnt vmcnt(0)
	v_pk_mul_f32 v[204:205], v[204:205], v[116:117]
	v_pk_mul_f32 v[206:207], v[206:207], v[118:119]
	v_pk_fma_f32 v[204:205], v[154:155], s[8:9], v[204:205] op_sel_hi:[1,0,1]
	v_pk_fma_f32 v[206:207], v[156:157], s[8:9], v[206:207] op_sel_hi:[1,0,1]
	global_store_dwordx4 v[228:229], v[204:207], off
	v_pk_mul_f32 v[88:89], v[88:89], v[120:121]
	v_pk_mul_f32 v[90:91], v[90:91], v[122:123]
	v_pk_fma_f32 v[88:89], v[158:159], s[8:9], v[88:89] op_sel_hi:[1,0,1]
	v_pk_fma_f32 v[90:91], v[160:161], s[8:9], v[90:91] op_sel_hi:[1,0,1]
	global_store_dwordx4 v[228:229], v[88:91], off offset:64
	v_pk_mul_f32 v[84:85], v[84:85], v[124:125]
	v_pk_mul_f32 v[86:87], v[86:87], v[126:127]
	v_pk_fma_f32 v[84:85], v[162:163], s[8:9], v[84:85] op_sel_hi:[1,0,1]
	v_pk_fma_f32 v[86:87], v[164:165], s[8:9], v[86:87] op_sel_hi:[1,0,1]
	global_store_dwordx4 v[228:229], v[84:87], off offset:128
	v_pk_mul_f32 v[80:81], v[80:81], v[134:135]
	v_pk_mul_f32 v[82:83], v[82:83], v[136:137]
	v_pk_fma_f32 v[80:81], v[166:167], s[8:9], v[80:81] op_sel_hi:[1,0,1]
	v_pk_fma_f32 v[82:83], v[168:169], s[8:9], v[82:83] op_sel_hi:[1,0,1]
	global_store_dwordx4 v[228:229], v[80:83], off offset:192
	v_pk_mul_f32 v[76:77], v[76:77], v[138:139]
	v_pk_mul_f32 v[78:79], v[78:79], v[140:141]
	v_pk_fma_f32 v[76:77], v[208:209], s[8:9], v[76:77] op_sel_hi:[1,0,1]
	v_pk_fma_f32 v[78:79], v[210:211], s[8:9], v[78:79] op_sel_hi:[1,0,1]
	global_store_dwordx4 v[230:231], v[76:79], off
	v_pk_mul_f32 v[72:73], v[72:73], v[200:201]
	v_pk_mul_f32 v[74:75], v[74:75], v[202:203]
	v_pk_fma_f32 v[72:73], v[212:213], s[8:9], v[72:73] op_sel_hi:[1,0,1]
	v_pk_fma_f32 v[74:75], v[214:215], s[8:9], v[74:75] op_sel_hi:[1,0,1]
	global_store_dwordx4 v[230:231], v[72:75], off offset:64
	v_pk_mul_f32 v[68:69], v[68:69], v[92:93]
	v_pk_mul_f32 v[70:71], v[70:71], v[94:95]
	v_pk_fma_f32 v[68:69], v[216:217], s[8:9], v[68:69] op_sel_hi:[1,0,1]
	v_pk_fma_f32 v[70:71], v[218:219], s[8:9], v[70:71] op_sel_hi:[1,0,1]
	global_store_dwordx4 v[230:231], v[68:71], off offset:128
	v_pk_mul_f32 v[64:65], v[64:65], v[244:245]
	v_pk_mul_f32 v[66:67], v[66:67], v[246:247]
	v_pk_fma_f32 v[64:65], v[220:221], s[8:9], v[64:65] op_sel_hi:[1,0,1]
	v_pk_fma_f32 v[66:67], v[222:223], s[8:9], v[66:67] op_sel_hi:[1,0,1]
	global_store_dwordx4 v[230:231], v[64:67], off offset:192
	v_add_u32_e32 v254, 32, v237
	v_add_u32_e32 v236, 0xfffff000, v254
	v_cmp_lt_i32_e32 vcc, 0xfff, v254
	v_lshrrev_b32_e32 v236, 10, v236
	v_lshlrev_b32_e32 v254, 12, v254
	v_add_u32_e32 v236, 1, v236
	v_cndmask_b32_e32 v236, 0, v236, vcc
	v_lshl_add_u64 v[224:225], v[254:255], 0, v[248:249]
	v_lshl_add_u64 v[228:229], v[254:255], 0, v[250:251]
	v_add_u32_e32 v236, s4, v236
	v_mad_i64_i32 v[232:233], s[0:1], v236, s33, v[252:253]
	v_add_u32_e32 v254, 48, v237
	v_add_u32_e32 v236, 0xfffff000, v254
	v_cmp_lt_i32_e32 vcc, 0xfff, v254
	v_lshrrev_b32_e32 v236, 10, v236
	v_lshlrev_b32_e32 v254, 12, v254
	v_add_u32_e32 v236, 1, v236
	v_cndmask_b32_e32 v236, 0, v236, vcc
	v_lshl_add_u64 v[226:227], v[254:255], 0, v[248:249]
	v_lshl_add_u64 v[230:231], v[254:255], 0, v[250:251]
	v_add_u32_e32 v236, s4, v236
	v_mad_i64_i32 v[234:235], s[0:1], v236, s33, v[252:253]
	global_load_dwordx4 v[154:157], v[224:225], off
	global_load_dwordx4 v[116:119], v[232:233], off
	global_load_dwordx4 v[158:161], v[224:225], off offset:64
	global_load_dwordx4 v[120:123], v[232:233], off offset:64
	global_load_dwordx4 v[162:165], v[224:225], off offset:128
	global_load_dwordx4 v[124:127], v[232:233], off offset:128
	global_load_dwordx4 v[166:169], v[224:225], off offset:192
	global_load_dwordx4 v[134:137], v[232:233], off offset:192
	global_load_dwordx4 v[208:211], v[226:227], off
	global_load_dwordx4 v[138:141], v[234:235], off
	global_load_dwordx4 v[212:215], v[226:227], off offset:64
	global_load_dwordx4 v[200:203], v[234:235], off offset:64
	global_load_dwordx4 v[216:219], v[226:227], off offset:128
	global_load_dwordx4 v[92:95], v[234:235], off offset:128
	global_load_dwordx4 v[220:223], v[226:227], off offset:192
	global_load_dwordx4 v[244:247], v[234:235], off offset:192
	s_waitcnt vmcnt(0)
	v_pk_mul_f32 v[60:61], v[60:61], v[116:117]
	v_pk_mul_f32 v[62:63], v[62:63], v[118:119]
	v_pk_fma_f32 v[60:61], v[154:155], s[8:9], v[60:61] op_sel_hi:[1,0,1]
	v_pk_fma_f32 v[62:63], v[156:157], s[8:9], v[62:63] op_sel_hi:[1,0,1]
	global_store_dwordx4 v[228:229], v[60:63], off
	v_pk_mul_f32 v[56:57], v[56:57], v[120:121]
	v_pk_mul_f32 v[58:59], v[58:59], v[122:123]
	v_pk_fma_f32 v[56:57], v[158:159], s[8:9], v[56:57] op_sel_hi:[1,0,1]
	v_pk_fma_f32 v[58:59], v[160:161], s[8:9], v[58:59] op_sel_hi:[1,0,1]
	global_store_dwordx4 v[228:229], v[56:59], off offset:64
	v_pk_mul_f32 v[52:53], v[52:53], v[124:125]
	v_pk_mul_f32 v[54:55], v[54:55], v[126:127]
	v_pk_fma_f32 v[52:53], v[162:163], s[8:9], v[52:53] op_sel_hi:[1,0,1]
	v_pk_fma_f32 v[54:55], v[164:165], s[8:9], v[54:55] op_sel_hi:[1,0,1]
	global_store_dwordx4 v[228:229], v[52:55], off offset:128
	v_pk_mul_f32 v[48:49], v[48:49], v[134:135]
	v_pk_mul_f32 v[50:51], v[50:51], v[136:137]
	v_pk_fma_f32 v[48:49], v[166:167], s[8:9], v[48:49] op_sel_hi:[1,0,1]
	v_pk_fma_f32 v[50:51], v[168:169], s[8:9], v[50:51] op_sel_hi:[1,0,1]
	global_store_dwordx4 v[228:229], v[48:51], off offset:192
	v_pk_mul_f32 v[44:45], v[44:45], v[138:139]
	v_pk_mul_f32 v[46:47], v[46:47], v[140:141]
	v_pk_fma_f32 v[44:45], v[208:209], s[8:9], v[44:45] op_sel_hi:[1,0,1]
	v_pk_fma_f32 v[46:47], v[210:211], s[8:9], v[46:47] op_sel_hi:[1,0,1]
	global_store_dwordx4 v[230:231], v[44:47], off
	v_pk_mul_f32 v[40:41], v[40:41], v[200:201]
	v_pk_mul_f32 v[42:43], v[42:43], v[202:203]
	v_pk_fma_f32 v[40:41], v[212:213], s[8:9], v[40:41] op_sel_hi:[1,0,1]
	v_pk_fma_f32 v[42:43], v[214:215], s[8:9], v[42:43] op_sel_hi:[1,0,1]
	global_store_dwordx4 v[230:231], v[40:43], off offset:64
	v_pk_mul_f32 v[36:37], v[36:37], v[92:93]
	v_pk_mul_f32 v[38:39], v[38:39], v[94:95]
	v_pk_fma_f32 v[36:37], v[216:217], s[8:9], v[36:37] op_sel_hi:[1,0,1]
	v_pk_fma_f32 v[38:39], v[218:219], s[8:9], v[38:39] op_sel_hi:[1,0,1]
	global_store_dwordx4 v[230:231], v[36:39], off offset:128
	v_pk_mul_f32 v[32:33], v[32:33], v[244:245]
	v_pk_mul_f32 v[34:35], v[34:35], v[246:247]
	v_pk_fma_f32 v[32:33], v[220:221], s[8:9], v[32:33] op_sel_hi:[1,0,1]
	v_pk_fma_f32 v[34:35], v[222:223], s[8:9], v[34:35] op_sel_hi:[1,0,1]
	global_store_dwordx4 v[230:231], v[32:35], off offset:192
	v_add_u32_e32 v254, 64, v237
	v_add_u32_e32 v236, 0xfffff000, v254
	v_cmp_lt_i32_e32 vcc, 0xfff, v254
	v_lshrrev_b32_e32 v236, 10, v236
	v_lshlrev_b32_e32 v254, 12, v254
	v_add_u32_e32 v236, 1, v236
	v_cndmask_b32_e32 v236, 0, v236, vcc
	v_lshl_add_u64 v[224:225], v[254:255], 0, v[248:249]
	v_lshl_add_u64 v[228:229], v[254:255], 0, v[250:251]
	v_add_u32_e32 v236, s4, v236
	v_mad_i64_i32 v[232:233], s[0:1], v236, s33, v[252:253]
	v_add_u32_e32 v254, 80, v237
	v_add_u32_e32 v236, 0xfffff000, v254
	v_cmp_lt_i32_e32 vcc, 0xfff, v254
	v_lshrrev_b32_e32 v236, 10, v236
	v_lshlrev_b32_e32 v254, 12, v254
	v_add_u32_e32 v236, 1, v236
	v_cndmask_b32_e32 v236, 0, v236, vcc
	v_lshl_add_u64 v[226:227], v[254:255], 0, v[248:249]
	v_lshl_add_u64 v[230:231], v[254:255], 0, v[250:251]
	v_add_u32_e32 v236, s4, v236
	v_mad_i64_i32 v[234:235], s[0:1], v236, s33, v[252:253]
	global_load_dwordx4 v[154:157], v[224:225], off
	global_load_dwordx4 v[116:119], v[232:233], off
	global_load_dwordx4 v[158:161], v[224:225], off offset:64
	global_load_dwordx4 v[120:123], v[232:233], off offset:64
	global_load_dwordx4 v[162:165], v[224:225], off offset:128
	global_load_dwordx4 v[124:127], v[232:233], off offset:128
	global_load_dwordx4 v[166:169], v[224:225], off offset:192
	global_load_dwordx4 v[134:137], v[232:233], off offset:192
	global_load_dwordx4 v[208:211], v[226:227], off
	global_load_dwordx4 v[138:141], v[234:235], off
	global_load_dwordx4 v[212:215], v[226:227], off offset:64
	global_load_dwordx4 v[200:203], v[234:235], off offset:64
	global_load_dwordx4 v[216:219], v[226:227], off offset:128
	global_load_dwordx4 v[92:95], v[234:235], off offset:128
	global_load_dwordx4 v[220:223], v[226:227], off offset:192
	global_load_dwordx4 v[244:247], v[234:235], off offset:192
	s_waitcnt vmcnt(0)
	v_pk_mul_f32 v[28:29], v[28:29], v[116:117]
	v_pk_mul_f32 v[30:31], v[30:31], v[118:119]
	v_pk_fma_f32 v[28:29], v[154:155], s[8:9], v[28:29] op_sel_hi:[1,0,1]
	v_pk_fma_f32 v[30:31], v[156:157], s[8:9], v[30:31] op_sel_hi:[1,0,1]
	global_store_dwordx4 v[228:229], v[28:31], off
	v_pk_mul_f32 v[24:25], v[24:25], v[120:121]
	v_pk_mul_f32 v[26:27], v[26:27], v[122:123]
	v_pk_fma_f32 v[24:25], v[158:159], s[8:9], v[24:25] op_sel_hi:[1,0,1]
	v_pk_fma_f32 v[26:27], v[160:161], s[8:9], v[26:27] op_sel_hi:[1,0,1]
	global_store_dwordx4 v[228:229], v[24:27], off offset:64
	v_pk_mul_f32 v[20:21], v[20:21], v[124:125]
	v_pk_mul_f32 v[22:23], v[22:23], v[126:127]
	v_pk_fma_f32 v[20:21], v[162:163], s[8:9], v[20:21] op_sel_hi:[1,0,1]
	v_pk_fma_f32 v[22:23], v[164:165], s[8:9], v[22:23] op_sel_hi:[1,0,1]
	global_store_dwordx4 v[228:229], v[20:23], off offset:128
	v_pk_mul_f32 v[16:17], v[16:17], v[134:135]
	v_pk_mul_f32 v[18:19], v[18:19], v[136:137]
	v_pk_fma_f32 v[16:17], v[166:167], s[8:9], v[16:17] op_sel_hi:[1,0,1]
	v_pk_fma_f32 v[18:19], v[168:169], s[8:9], v[18:19] op_sel_hi:[1,0,1]
	global_store_dwordx4 v[228:229], v[16:19], off offset:192
	v_pk_mul_f32 v[12:13], v[12:13], v[138:139]
	v_pk_mul_f32 v[14:15], v[14:15], v[140:141]
	v_pk_fma_f32 v[12:13], v[208:209], s[8:9], v[12:13] op_sel_hi:[1,0,1]
	v_pk_fma_f32 v[14:15], v[210:211], s[8:9], v[14:15] op_sel_hi:[1,0,1]
	global_store_dwordx4 v[230:231], v[12:15], off
	v_pk_mul_f32 v[8:9], v[8:9], v[200:201]
	v_pk_mul_f32 v[10:11], v[10:11], v[202:203]
	v_pk_fma_f32 v[8:9], v[212:213], s[8:9], v[8:9] op_sel_hi:[1,0,1]
	v_pk_fma_f32 v[10:11], v[214:215], s[8:9], v[10:11] op_sel_hi:[1,0,1]
	global_store_dwordx4 v[230:231], v[8:11], off offset:64
	v_pk_mul_f32 v[4:5], v[4:5], v[92:93]
	v_pk_mul_f32 v[6:7], v[6:7], v[94:95]
	v_pk_fma_f32 v[4:5], v[216:217], s[8:9], v[4:5] op_sel_hi:[1,0,1]
	v_pk_fma_f32 v[6:7], v[218:219], s[8:9], v[6:7] op_sel_hi:[1,0,1]
	global_store_dwordx4 v[230:231], v[4:7], off offset:128
	v_pk_mul_f32 v[0:1], v[0:1], v[244:245]
	v_pk_mul_f32 v[2:3], v[2:3], v[246:247]
	v_pk_fma_f32 v[0:1], v[220:221], s[8:9], v[0:1] op_sel_hi:[1,0,1]
	v_pk_fma_f32 v[2:3], v[222:223], s[8:9], v[2:3] op_sel_hi:[1,0,1]
	global_store_dwordx4 v[230:231], v[0:3], off offset:192
	v_readlane_b32 s9, v242, 26
	v_readlane_b32 s10, v242, 27
	v_readlane_b32 s11, v242, 28
	v_readlane_b32 s12, v242, 29
	v_readlane_b32 s13, v242, 30
	v_readlane_b32 s14, v242, 31
	v_readlane_b32 s15, v242, 32
	v_readlane_b32 s16, v242, 33
	v_readlane_b32 s17, v242, 34
	v_readlane_b32 s18, v242, 35
	v_readlane_b32 s19, v242, 36
	v_readlane_b32 s20, v242, 37
	v_readlane_b32 s21, v242, 38
	v_readlane_b32 s22, v242, 39
	v_readlane_b32 s23, v242, 40
	s_mov_b64 s[24:25], 0x5000
	s_movk_i32 s6, 0xfff
	s_waitcnt lgkmcnt(0)
	s_barrier
	s_cmpk_gt_i32 s5, 0xff
	s_cbranch_scc0 .LBB0_52

.LBB0_128:
	s_mul_i32 s5, s10, 0x5000
	v_add_u32_e32 v156, s5, v142
	v_lshl_add_u64 v[126:127], v[124:125], 0, s[6:7]
	v_readfirstlane_b32 s5, v156
	v_add_u32_e32 v136, 0x1000, v156
	v_lshl_add_u64 v[134:135], v[126:127], 0, s[2:3]
	s_mov_b32 m0, s5
	v_lshl_add_u64 v[138:139], v[122:123], 0, s[6:7]
	v_readfirstlane_b32 s5, v136
	s_waitcnt vmcnt(5)
	s_barrier
	global_load_lds_dwordx4 v[134:135], off
	v_lshl_add_u64 v[134:135], v[138:139], 0, s[2:3]
	s_mov_b32 m0, s5
	v_add_u32_e32 v140, 0x2000, v156
	global_load_lds_dwordx4 v[134:135], off
	v_lshl_add_u64 v[134:135], v[120:121], 0, s[6:7]
	v_readfirstlane_b32 s5, v140
	v_lshl_add_u64 v[136:137], v[134:135], 0, s[2:3]
	s_mov_b32 m0, s5
	v_add_u32_e32 v154, 0x3000, v156
	global_load_lds_dwordx4 v[136:137], off
	v_lshl_add_u64 v[136:137], v[118:119], 0, s[6:7]
	v_readfirstlane_b32 s5, v154
	v_lshl_add_u64 v[140:141], v[136:137], 0, s[2:3]
	s_mov_b32 m0, s5
	v_add_u32_e32 v156, 0x4000, v156
	global_load_lds_dwordx4 v[140:141], off
	v_lshl_add_u64 v[140:141], v[116:117], 0, s[6:7]
	v_readfirstlane_b32 s5, v156
	v_lshl_add_u64 v[154:155], v[140:141], 0, s[2:3]
	s_mov_b32 m0, s5
	s_mul_i32 s5, s1, 0x5000
	global_load_lds_dwordx4 v[154:155], off
	v_or_b32_e32 v154, s5, v147
	v_add_u32_e32 v170, v154, v128
	ds_read_b128 v[154:157], v170
	ds_read_b128 v[158:161], v170 offset:1024
	ds_read_b128 v[162:165], v170 offset:2048
	ds_read_b128 v[166:169], v170 offset:3072
	ds_read_b128 v[200:203], v170 offset:4096
	ds_read_b128 v[204:207], v170 offset:5120
	v_or_b32_e32 v170, s5, v149
	v_add_u32_e32 v170, v170, v148
	s_add_i32 s1, s1, 1
	s_add_i32 s10, s10, 1
	ds_read_b128 v[208:211], v170 offset:12288
	ds_read_b128 v[212:215], v170 offset:13312
	ds_read_b128 v[216:219], v170 offset:14336
	ds_read_b128 v[220:223], v170 offset:15360
	s_cmp_lg_u32 s1, 3
	s_cselect_b32 s1, s1, 0
	s_cmp_lg_u32 s10, 3
	s_cselect_b32 s5, s10, 0
	s_mul_i32 s10, s5, 0x5000
	s_waitcnt lgkmcnt(0)
	v_mfma_f32_16x16x32_bf16 v[92:95], v[208:211], v[154:157], v[92:95]
	v_lshl_add_u64 v[126:127], v[126:127], 0, s[30:31]
	s_waitcnt vmcnt(5)
	s_barrier
	v_mfma_f32_16x16x32_bf16 v[88:91], v[212:215], v[154:157], v[88:91]
	s_add_i32 s5, s5, 1
	v_mfma_f32_16x16x32_bf16 v[84:87], v[216:219], v[154:157], v[84:87]
	v_mfma_f32_16x16x32_bf16 v[80:83], v[220:223], v[154:157], v[80:83]
	v_add_u32_e32 v154, s10, v142
	s_nop 0
	v_readfirstlane_b32 s10, v154
	s_mov_b32 m0, s10
	v_mfma_f32_16x16x32_bf16 v[76:79], v[208:211], v[158:161], v[76:79]
	global_load_lds_dwordx4 v[126:127], off
	v_lshl_add_u64 v[126:127], v[138:139], 0, s[30:31]
	v_add_u32_e32 v138, 0x1000, v154
	v_mfma_f32_16x16x32_bf16 v[72:75], v[212:215], v[158:161], v[72:75]
	v_readfirstlane_b32 s10, v138
	s_mov_b32 m0, s10
	s_nop 0
	global_load_lds_dwordx4 v[126:127], off
	v_lshl_add_u64 v[126:127], v[134:135], 0, s[30:31]
	v_add_u32_e32 v134, 0x2000, v154
	v_mfma_f32_16x16x32_bf16 v[68:71], v[216:219], v[158:161], v[68:71]
	v_readfirstlane_b32 s10, v134
	v_add_u32_e32 v134, 0x3000, v154
	s_mov_b32 m0, s10
	v_readfirstlane_b32 s10, v134
	v_add_u32_e32 v134, 0x4000, v154
	global_load_lds_dwordx4 v[126:127], off
	v_lshl_add_u64 v[126:127], v[136:137], 0, s[30:31]
	s_mov_b32 m0, s10
	v_readfirstlane_b32 s10, v134
	global_load_lds_dwordx4 v[126:127], off
	v_lshl_add_u64 v[126:127], v[140:141], 0, s[30:31]
	s_mov_b32 m0, s10
	s_mul_i32 s10, s1, 0x5000
	global_load_lds_dwordx4 v[126:127], off
	v_or_b32_e32 v126, s10, v147
	v_add_u32_e32 v126, v126, v128
	v_mfma_f32_16x16x32_bf16 v[64:67], v[220:223], v[158:161], v[64:67]
	s_add_i32 s1, s1, 1
	s_cmp_lg_u32 s1, 3
	s_cselect_b32 s1, s1, 0
	v_mfma_f32_16x16x32_bf16 v[60:63], v[208:211], v[162:165], v[60:63]
	s_cmp_lg_u32 s5, 3
	v_mfma_f32_16x16x32_bf16 v[56:59], v[212:215], v[162:165], v[56:59]
	v_mfma_f32_16x16x32_bf16 v[52:55], v[216:219], v[162:165], v[52:55]
	v_mfma_f32_16x16x32_bf16 v[48:51], v[220:223], v[162:165], v[48:51]
	v_mfma_f32_16x16x32_bf16 v[44:47], v[208:211], v[166:169], v[44:47]
	v_mfma_f32_16x16x32_bf16 v[40:43], v[212:215], v[166:169], v[40:43]
	v_mfma_f32_16x16x32_bf16 v[36:39], v[216:219], v[166:169], v[36:39]
	v_mfma_f32_16x16x32_bf16 v[32:35], v[220:223], v[166:169], v[32:35]
	ds_read_b128 v[134:137], v126
	ds_read_b128 v[138:141], v126 offset:1024
	ds_read_b128 v[154:157], v126 offset:2048
	ds_read_b128 v[158:161], v126 offset:3072
	ds_read_b128 v[162:165], v126 offset:4096
	ds_read_b128 v[166:169], v126 offset:5120
	v_or_b32_e32 v126, s10, v149
	v_add_u32_e32 v126, v126, v148
	v_mfma_f32_16x16x32_bf16 v[28:31], v[208:211], v[200:203], v[28:31]
	s_cselect_b32 s10, s5, 0
	s_add_u32 s6, s6, 0x80
	s_addc_u32 s7, s7, 0
	v_mfma_f32_16x16x32_bf16 v[24:27], v[212:215], v[200:203], v[24:27]
	s_cmpk_eq_i32 s6, 0x780
	v_mfma_f32_16x16x32_bf16 v[20:23], v[216:219], v[200:203], v[20:23]
	v_mfma_f32_16x16x32_bf16 v[16:19], v[220:223], v[200:203], v[16:19]
	v_mfma_f32_16x16x32_bf16 v[8:11], v[208:211], v[204:207], v[8:11]
	v_mfma_f32_16x16x32_bf16 v[4:7], v[212:215], v[204:207], v[4:7]
	v_mfma_f32_16x16x32_bf16 v[12:15], v[216:219], v[204:207], v[12:15]
	v_mfma_f32_16x16x32_bf16 v[0:3], v[220:223], v[204:207], v[0:3]
	ds_read_b128 v[200:203], v126 offset:12288
	ds_read_b128 v[204:207], v126 offset:13312
	ds_read_b128 v[208:211], v126 offset:14336
	ds_read_b128 v[212:215], v126 offset:15360
	s_waitcnt lgkmcnt(0)
	v_mfma_f32_16x16x32_bf16 v[92:95], v[200:203], v[134:137], v[92:95]
	v_mfma_f32_16x16x32_bf16 v[88:91], v[204:207], v[134:137], v[88:91]
	v_mfma_f32_16x16x32_bf16 v[84:87], v[208:211], v[134:137], v[84:87]
	v_mfma_f32_16x16x32_bf16 v[80:83], v[212:215], v[134:137], v[80:83]
	v_mfma_f32_16x16x32_bf16 v[76:79], v[200:203], v[138:141], v[76:79]
	v_mfma_f32_16x16x32_bf16 v[72:75], v[204:207], v[138:141], v[72:75]
	v_mfma_f32_16x16x32_bf16 v[68:71], v[208:211], v[138:141], v[68:71]
	v_mfma_f32_16x16x32_bf16 v[64:67], v[212:215], v[138:141], v[64:67]
	v_mfma_f32_16x16x32_bf16 v[60:63], v[200:203], v[154:157], v[60:63]
	v_mfma_f32_16x16x32_bf16 v[56:59], v[204:207], v[154:157], v[56:59]
	v_mfma_f32_16x16x32_bf16 v[52:55], v[208:211], v[154:157], v[52:55]
	v_mfma_f32_16x16x32_bf16 v[48:51], v[212:215], v[154:157], v[48:51]
	v_mfma_f32_16x16x32_bf16 v[44:47], v[200:203], v[158:161], v[44:47]
	v_mfma_f32_16x16x32_bf16 v[40:43], v[204:207], v[158:161], v[40:43]
	v_mfma_f32_16x16x32_bf16 v[36:39], v[208:211], v[158:161], v[36:39]
	v_mfma_f32_16x16x32_bf16 v[32:35], v[212:215], v[158:161], v[32:35]
	v_mfma_f32_16x16x32_bf16 v[28:31], v[200:203], v[162:165], v[28:31]
	v_mfma_f32_16x16x32_bf16 v[24:27], v[204:207], v[162:165], v[24:27]
	v_mfma_f32_16x16x32_bf16 v[20:23], v[208:211], v[162:165], v[20:23]
	v_mfma_f32_16x16x32_bf16 v[16:19], v[212:215], v[162:165], v[16:19]
	v_mfma_f32_16x16x32_bf16 v[8:11], v[200:203], v[166:169], v[8:11]
	v_mfma_f32_16x16x32_bf16 v[4:7], v[204:207], v[166:169], v[4:7]
	v_mfma_f32_16x16x32_bf16 v[12:15], v[208:211], v[166:169], v[12:15]
	v_mfma_f32_16x16x32_bf16 v[0:3], v[212:215], v[166:169], v[0:3]
	s_cbranch_scc0 .LBB0_128
	v_add_u32_e32 v170, v147, v128
	v_add_u32_e32 v172, v149, v148
	s_waitcnt vmcnt(5)
	s_barrier
	ds_read_b128 v[116:119], v170
	ds_read_b128 v[120:123], v170 offset:1024
	ds_read_b128 v[124:127], v170 offset:2048
	ds_read_b128 v[134:137], v170 offset:3072
	ds_read_b128 v[138:141], v170 offset:4096
	ds_read_b128 v[154:157], v170 offset:5120
	ds_read_b128 v[158:161], v172 offset:12288
	ds_read_b128 v[162:165], v172 offset:13312
	ds_read_b128 v[166:169], v172 offset:14336
	ds_read_b128 v[200:203], v172 offset:15360
	s_waitcnt lgkmcnt(0)
	v_mfma_f32_16x16x32_bf16 v[92:95], v[158:161], v[116:119], v[92:95]
	s_waitcnt vmcnt(0)
	s_barrier
	v_readlane_b32 s12, v243, 5
	v_mfma_f32_16x16x32_bf16 v[88:91], v[162:165], v[116:119], v[88:91]
	v_readlane_b32 s18, v243, 11
	v_readlane_b32 s19, v243, 12
	v_readlane_b32 s13, v243, 6
	v_mfma_f32_16x16x32_bf16 v[84:87], v[166:169], v[116:119], v[84:87]
	v_readlane_b32 s14, v243, 7
	v_readlane_b32 s15, v243, 8
	v_readlane_b32 s16, v243, 9
	v_mfma_f32_16x16x32_bf16 v[80:83], v[200:203], v[116:119], v[80:83]
	v_readlane_b32 s17, v243, 10
	v_readlane_b32 s20, v243, 13
	v_readlane_b32 s21, v243, 14
	v_mfma_f32_16x16x32_bf16 v[76:79], v[158:161], v[120:123], v[76:79]
	v_readlane_b32 s22, v243, 15
	v_readlane_b32 s23, v243, 16
	v_readlane_b32 s24, v243, 17
	v_mfma_f32_16x16x32_bf16 v[72:75], v[162:165], v[120:123], v[72:75]
	v_readlane_b32 s25, v243, 18
	v_readlane_b32 s26, v243, 19
	v_readlane_b32 s27, v243, 20
	v_mfma_f32_16x16x32_bf16 v[68:71], v[166:169], v[120:123], v[68:71]
	s_mov_b64 s[10:11], 0x2000
	s_mov_b32 s6, 0x3fd744fd
	s_add_i32 s9, s9, s51
	v_mfma_f32_16x16x32_bf16 v[64:67], v[200:203], v[120:123], v[64:67]
	s_cmpk_gt_i32 s9, 0xff
	v_mfma_f32_16x16x32_bf16 v[60:63], v[158:161], v[124:127], v[60:63]
	v_mfma_f32_16x16x32_bf16 v[56:59], v[162:165], v[124:127], v[56:59]
	v_mfma_f32_16x16x32_bf16 v[52:55], v[166:169], v[124:127], v[52:55]
	v_mfma_f32_16x16x32_bf16 v[48:51], v[200:203], v[124:127], v[48:51]
	v_mfma_f32_16x16x32_bf16 v[44:47], v[158:161], v[134:137], v[44:47]
	v_mfma_f32_16x16x32_bf16 v[40:43], v[162:165], v[134:137], v[40:43]
	v_mfma_f32_16x16x32_bf16 v[36:39], v[166:169], v[134:137], v[36:39]
	v_mfma_f32_16x16x32_bf16 v[32:35], v[200:203], v[134:137], v[32:35]
	v_mfma_f32_16x16x32_bf16 v[28:31], v[158:161], v[138:141], v[28:31]
	v_mfma_f32_16x16x32_bf16 v[24:27], v[162:165], v[138:141], v[24:27]
	v_mfma_f32_16x16x32_bf16 v[20:23], v[166:169], v[138:141], v[20:23]
	v_mfma_f32_16x16x32_bf16 v[16:19], v[200:203], v[138:141], v[16:19]
	v_mfma_f32_16x16x32_bf16 v[8:11], v[158:161], v[154:157], v[8:11]
	v_mfma_f32_16x16x32_bf16 v[4:7], v[162:165], v[154:157], v[4:7]
	v_mfma_f32_16x16x32_bf16 v[116:119], v[166:169], v[154:157], v[12:15]
	v_mfma_f32_16x16x32_bf16 v[0:3], v[200:203], v[154:157], v[0:3]
	s_nop 1
	ds_read_b128 v[12:15], v170 offset:20480
	ds_read_b128 v[120:123], v170 offset:21504
	ds_read_b128 v[124:127], v170 offset:22528
	ds_read_b128 v[134:137], v170 offset:23552
	ds_read_b128 v[138:141], v170 offset:24576
	ds_read_b128 v[154:157], v170 offset:25600
	ds_read_b128 v[158:161], v172 offset:32768
	ds_read_b128 v[162:165], v172 offset:33792
	ds_read_b128 v[166:169], v172 offset:34816
	ds_read_b128 v[200:203], v172 offset:35840
	s_waitcnt lgkmcnt(0)
	v_mfma_f32_16x16x32_bf16 v[76:79], v[158:161], v[120:123], v[76:79]
	v_mfma_f32_16x16x32_bf16 v[72:75], v[162:165], v[120:123], v[72:75]
	v_mfma_f32_16x16x32_bf16 v[68:71], v[166:169], v[120:123], v[68:71]
	v_mfma_f32_16x16x32_bf16 v[64:67], v[200:203], v[120:123], v[64:67]
	v_mfma_f32_16x16x32_bf16 v[204:207], v[158:161], v[12:15], v[92:95]
	v_mfma_f32_16x16x32_bf16 v[88:91], v[162:165], v[12:15], v[88:91]
	v_mfma_f32_16x16x32_bf16 v[84:87], v[166:169], v[12:15], v[84:87]
	v_mfma_f32_16x16x32_bf16 v[80:83], v[200:203], v[12:15], v[80:83]
	v_mfma_f32_16x16x32_bf16 v[12:15], v[158:161], v[154:157], v[8:11]
	v_mfma_f32_16x16x32_bf16 v[8:11], v[162:165], v[154:157], v[4:7]
	v_mfma_f32_16x16x32_bf16 v[4:7], v[166:169], v[154:157], v[116:119]
	v_mfma_f32_16x16x32_bf16 v[28:31], v[158:161], v[138:141], v[28:31]
	v_mfma_f32_16x16x32_bf16 v[24:27], v[162:165], v[138:141], v[24:27]
	v_mfma_f32_16x16x32_bf16 v[20:23], v[166:169], v[138:141], v[20:23]
	v_mfma_f32_16x16x32_bf16 v[16:19], v[200:203], v[138:141], v[16:19]
	v_mfma_f32_16x16x32_bf16 v[60:63], v[158:161], v[124:127], v[60:63]
	v_mfma_f32_16x16x32_bf16 v[56:59], v[162:165], v[124:127], v[56:59]
	v_mfma_f32_16x16x32_bf16 v[52:55], v[166:169], v[124:127], v[52:55]
	v_mfma_f32_16x16x32_bf16 v[48:51], v[200:203], v[124:127], v[48:51]
	v_mfma_f32_16x16x32_bf16 v[44:47], v[158:161], v[134:137], v[44:47]
	v_mfma_f32_16x16x32_bf16 v[40:43], v[162:165], v[134:137], v[40:43]
	v_mfma_f32_16x16x32_bf16 v[36:39], v[166:169], v[134:137], v[36:39]
	v_mfma_f32_16x16x32_bf16 v[32:35], v[200:203], v[134:137], v[32:35]
	v_mfma_f32_16x16x32_bf16 v[0:3], v[200:203], v[154:157], v[0:3]
	v_readlane_b32 s10, v242, 25
	v_readlane_b32 s11, v242, 26
	v_readlane_b32 s12, v242, 29
	v_readlane_b32 s13, v242, 30
	v_readlane_b32 s14, v243, 11
	v_readlane_b32 s15, v243, 12
	s_mov_b32 s6, 0x3fd744fd
	v_add_u32_e32 v236, s0, v145
	v_or_b32_e32 v254, s4, v146
	v_mov_b32_e32 v255, 0
	v_or_b32_e32 v237, v236, v133
	v_lshlrev_b64 v[254:255], 2, v[254:255]
	s_nop 0
	v_lshl_add_u64 v[248:249], s[10:11], 0, v[254:255]
	v_lshl_add_u64 v[250:251], s[12:13], 0, v[254:255]
	v_lshl_add_u64 v[252:253], s[14:15], 0, v[254:255]
	s_mov_b64 s[10:11], 0x2000
	v_mov_b32_e32 v255, 0
	v_lshl_add_u64 v[252:253], v[252:253], 0, s[10:11]
	v_add_u32_e32 v254, 0, v237
	v_add_u32_e32 v236, 0xfffff000, v254
	v_cmp_lt_i32_e32 vcc, 0xfff, v254
	v_lshrrev_b32_e32 v236, 10, v236
	v_lshlrev_b32_e32 v254, 12, v254
	v_add_u32_e32 v236, 1, v236
	v_cndmask_b32_e32 v236, 0, v236, vcc
	v_lshl_add_u64 v[224:225], v[254:255], 0, v[248:249]
	v_lshl_add_u64 v[228:229], v[254:255], 0, v[250:251]
	v_add_u32_e32 v236, s8, v236
	v_mad_i64_i32 v[232:233], s[0:1], v236, s33, v[252:253]
	v_add_u32_e32 v254, 16, v237
	v_add_u32_e32 v236, 0xfffff000, v254
	v_cmp_lt_i32_e32 vcc, 0xfff, v254
	v_lshrrev_b32_e32 v236, 10, v236
	v_lshlrev_b32_e32 v254, 12, v254
	v_add_u32_e32 v236, 1, v236
	v_cndmask_b32_e32 v236, 0, v236, vcc
	v_lshl_add_u64 v[226:227], v[254:255], 0, v[248:249]
	v_lshl_add_u64 v[230:231], v[254:255], 0, v[250:251]
	v_add_u32_e32 v236, s8, v236
	v_mad_i64_i32 v[234:235], s[0:1], v236, s33, v[252:253]
	global_load_dwordx4 v[154:157], v[224:225], off
	global_load_dwordx4 v[116:119], v[232:233], off
	global_load_dwordx4 v[158:161], v[224:225], off offset:64
	global_load_dwordx4 v[120:123], v[232:233], off offset:64
	global_load_dwordx4 v[162:165], v[224:225], off offset:128
	global_load_dwordx4 v[124:127], v[232:233], off offset:128
	global_load_dwordx4 v[166:169], v[224:225], off offset:192
	global_load_dwordx4 v[134:137], v[232:233], off offset:192
	global_load_dwordx4 v[208:211], v[226:227], off
	global_load_dwordx4 v[138:141], v[234:235], off
	global_load_dwordx4 v[212:215], v[226:227], off offset:64
	global_load_dwordx4 v[200:203], v[234:235], off offset:64
	global_load_dwordx4 v[216:219], v[226:227], off offset:128
	global_load_dwordx4 v[92:95], v[234:235], off offset:128
	global_load_dwordx4 v[220:223], v[226:227], off offset:192
	global_load_dwordx4 v[244:247], v[234:235], off offset:192
	s_waitcnt vmcnt(0)
	v_pk_mul_f32 v[204:205], v[204:205], v[116:117]
	v_pk_mul_f32 v[206:207], v[206:207], v[118:119]
	v_pk_fma_f32 v[204:205], v[154:155], s[6:7], v[204:205] op_sel_hi:[1,0,1]
	v_pk_fma_f32 v[206:207], v[156:157], s[6:7], v[206:207] op_sel_hi:[1,0,1]
	global_store_dwordx4 v[228:229], v[204:207], off
	v_pk_mul_f32 v[88:89], v[88:89], v[120:121]
	v_pk_mul_f32 v[90:91], v[90:91], v[122:123]
	v_pk_fma_f32 v[88:89], v[158:159], s[6:7], v[88:89] op_sel_hi:[1,0,1]
	v_pk_fma_f32 v[90:91], v[160:161], s[6:7], v[90:91] op_sel_hi:[1,0,1]
	global_store_dwordx4 v[228:229], v[88:91], off offset:64
	v_pk_mul_f32 v[84:85], v[84:85], v[124:125]
	v_pk_mul_f32 v[86:87], v[86:87], v[126:127]
	v_pk_fma_f32 v[84:85], v[162:163], s[6:7], v[84:85] op_sel_hi:[1,0,1]
	v_pk_fma_f32 v[86:87], v[164:165], s[6:7], v[86:87] op_sel_hi:[1,0,1]
	global_store_dwordx4 v[228:229], v[84:87], off offset:128
	v_pk_mul_f32 v[80:81], v[80:81], v[134:135]
	v_pk_mul_f32 v[82:83], v[82:83], v[136:137]
	v_pk_fma_f32 v[80:81], v[166:167], s[6:7], v[80:81] op_sel_hi:[1,0,1]
	v_pk_fma_f32 v[82:83], v[168:169], s[6:7], v[82:83] op_sel_hi:[1,0,1]
	global_store_dwordx4 v[228:229], v[80:83], off offset:192
	v_pk_mul_f32 v[76:77], v[76:77], v[138:139]
	v_pk_mul_f32 v[78:79], v[78:79], v[140:141]
	v_pk_fma_f32 v[76:77], v[208:209], s[6:7], v[76:77] op_sel_hi:[1,0,1]
	v_pk_fma_f32 v[78:79], v[210:211], s[6:7], v[78:79] op_sel_hi:[1,0,1]
	global_store_dwordx4 v[230:231], v[76:79], off
	v_pk_mul_f32 v[72:73], v[72:73], v[200:201]
	v_pk_mul_f32 v[74:75], v[74:75], v[202:203]
	v_pk_fma_f32 v[72:73], v[212:213], s[6:7], v[72:73] op_sel_hi:[1,0,1]
	v_pk_fma_f32 v[74:75], v[214:215], s[6:7], v[74:75] op_sel_hi:[1,0,1]
	global_store_dwordx4 v[230:231], v[72:75], off offset:64
	v_pk_mul_f32 v[68:69], v[68:69], v[92:93]
	v_pk_mul_f32 v[70:71], v[70:71], v[94:95]
	v_pk_fma_f32 v[68:69], v[216:217], s[6:7], v[68:69] op_sel_hi:[1,0,1]
	v_pk_fma_f32 v[70:71], v[218:219], s[6:7], v[70:71] op_sel_hi:[1,0,1]
	global_store_dwordx4 v[230:231], v[68:71], off offset:128
	v_pk_mul_f32 v[64:65], v[64:65], v[244:245]
	v_pk_mul_f32 v[66:67], v[66:67], v[246:247]
	v_pk_fma_f32 v[64:65], v[220:221], s[6:7], v[64:65] op_sel_hi:[1,0,1]
	v_pk_fma_f32 v[66:67], v[222:223], s[6:7], v[66:67] op_sel_hi:[1,0,1]
	global_store_dwordx4 v[230:231], v[64:67], off offset:192
	v_add_u32_e32 v254, 32, v237
	v_add_u32_e32 v236, 0xfffff000, v254
	v_cmp_lt_i32_e32 vcc, 0xfff, v254
	v_lshrrev_b32_e32 v236, 10, v236
	v_lshlrev_b32_e32 v254, 12, v254
	v_add_u32_e32 v236, 1, v236
	v_cndmask_b32_e32 v236, 0, v236, vcc
	v_lshl_add_u64 v[224:225], v[254:255], 0, v[248:249]
	v_lshl_add_u64 v[228:229], v[254:255], 0, v[250:251]
	v_add_u32_e32 v236, s8, v236
	v_mad_i64_i32 v[232:233], s[0:1], v236, s33, v[252:253]
	v_add_u32_e32 v254, 48, v237
	v_add_u32_e32 v236, 0xfffff000, v254
	v_cmp_lt_i32_e32 vcc, 0xfff, v254
	v_lshrrev_b32_e32 v236, 10, v236
	v_lshlrev_b32_e32 v254, 12, v254
	v_add_u32_e32 v236, 1, v236
	v_cndmask_b32_e32 v236, 0, v236, vcc
	v_lshl_add_u64 v[226:227], v[254:255], 0, v[248:249]
	v_lshl_add_u64 v[230:231], v[254:255], 0, v[250:251]
	v_add_u32_e32 v236, s8, v236
	v_mad_i64_i32 v[234:235], s[0:1], v236, s33, v[252:253]
	global_load_dwordx4 v[154:157], v[224:225], off
	global_load_dwordx4 v[116:119], v[232:233], off
	global_load_dwordx4 v[158:161], v[224:225], off offset:64
	global_load_dwordx4 v[120:123], v[232:233], off offset:64
	global_load_dwordx4 v[162:165], v[224:225], off offset:128
	global_load_dwordx4 v[124:127], v[232:233], off offset:128
	global_load_dwordx4 v[166:169], v[224:225], off offset:192
	global_load_dwordx4 v[134:137], v[232:233], off offset:192
	global_load_dwordx4 v[208:211], v[226:227], off
	global_load_dwordx4 v[138:141], v[234:235], off
	global_load_dwordx4 v[212:215], v[226:227], off offset:64
	global_load_dwordx4 v[200:203], v[234:235], off offset:64
	global_load_dwordx4 v[216:219], v[226:227], off offset:128
	global_load_dwordx4 v[92:95], v[234:235], off offset:128
	global_load_dwordx4 v[220:223], v[226:227], off offset:192
	global_load_dwordx4 v[244:247], v[234:235], off offset:192
	s_waitcnt vmcnt(0)
	v_pk_mul_f32 v[60:61], v[60:61], v[116:117]
	v_pk_mul_f32 v[62:63], v[62:63], v[118:119]
	v_pk_fma_f32 v[60:61], v[154:155], s[6:7], v[60:61] op_sel_hi:[1,0,1]
	v_pk_fma_f32 v[62:63], v[156:157], s[6:7], v[62:63] op_sel_hi:[1,0,1]
	global_store_dwordx4 v[228:229], v[60:63], off
	v_pk_mul_f32 v[56:57], v[56:57], v[120:121]
	v_pk_mul_f32 v[58:59], v[58:59], v[122:123]
	v_pk_fma_f32 v[56:57], v[158:159], s[6:7], v[56:57] op_sel_hi:[1,0,1]
	v_pk_fma_f32 v[58:59], v[160:161], s[6:7], v[58:59] op_sel_hi:[1,0,1]
	global_store_dwordx4 v[228:229], v[56:59], off offset:64
	v_pk_mul_f32 v[52:53], v[52:53], v[124:125]
	v_pk_mul_f32 v[54:55], v[54:55], v[126:127]
	v_pk_fma_f32 v[52:53], v[162:163], s[6:7], v[52:53] op_sel_hi:[1,0,1]
	v_pk_fma_f32 v[54:55], v[164:165], s[6:7], v[54:55] op_sel_hi:[1,0,1]
	global_store_dwordx4 v[228:229], v[52:55], off offset:128
	v_pk_mul_f32 v[48:49], v[48:49], v[134:135]
	v_pk_mul_f32 v[50:51], v[50:51], v[136:137]
	v_pk_fma_f32 v[48:49], v[166:167], s[6:7], v[48:49] op_sel_hi:[1,0,1]
	v_pk_fma_f32 v[50:51], v[168:169], s[6:7], v[50:51] op_sel_hi:[1,0,1]
	global_store_dwordx4 v[228:229], v[48:51], off offset:192
	v_pk_mul_f32 v[44:45], v[44:45], v[138:139]
	v_pk_mul_f32 v[46:47], v[46:47], v[140:141]
	v_pk_fma_f32 v[44:45], v[208:209], s[6:7], v[44:45] op_sel_hi:[1,0,1]
	v_pk_fma_f32 v[46:47], v[210:211], s[6:7], v[46:47] op_sel_hi:[1,0,1]
	global_store_dwordx4 v[230:231], v[44:47], off
	v_pk_mul_f32 v[40:41], v[40:41], v[200:201]
	v_pk_mul_f32 v[42:43], v[42:43], v[202:203]
	v_pk_fma_f32 v[40:41], v[212:213], s[6:7], v[40:41] op_sel_hi:[1,0,1]
	v_pk_fma_f32 v[42:43], v[214:215], s[6:7], v[42:43] op_sel_hi:[1,0,1]
	global_store_dwordx4 v[230:231], v[40:43], off offset:64
	v_pk_mul_f32 v[36:37], v[36:37], v[92:93]
	v_pk_mul_f32 v[38:39], v[38:39], v[94:95]
	v_pk_fma_f32 v[36:37], v[216:217], s[6:7], v[36:37] op_sel_hi:[1,0,1]
	v_pk_fma_f32 v[38:39], v[218:219], s[6:7], v[38:39] op_sel_hi:[1,0,1]
	global_store_dwordx4 v[230:231], v[36:39], off offset:128
	v_pk_mul_f32 v[32:33], v[32:33], v[244:245]
	v_pk_mul_f32 v[34:35], v[34:35], v[246:247]
	v_pk_fma_f32 v[32:33], v[220:221], s[6:7], v[32:33] op_sel_hi:[1,0,1]
	v_pk_fma_f32 v[34:35], v[222:223], s[6:7], v[34:35] op_sel_hi:[1,0,1]
	global_store_dwordx4 v[230:231], v[32:35], off offset:192
	v_add_u32_e32 v254, 64, v237
	v_add_u32_e32 v236, 0xfffff000, v254
	v_cmp_lt_i32_e32 vcc, 0xfff, v254
	v_lshrrev_b32_e32 v236, 10, v236
	v_lshlrev_b32_e32 v254, 12, v254
	v_add_u32_e32 v236, 1, v236
	v_cndmask_b32_e32 v236, 0, v236, vcc
	v_lshl_add_u64 v[224:225], v[254:255], 0, v[248:249]
	v_lshl_add_u64 v[228:229], v[254:255], 0, v[250:251]
	v_add_u32_e32 v236, s8, v236
	v_mad_i64_i32 v[232:233], s[0:1], v236, s33, v[252:253]
	v_add_u32_e32 v254, 80, v237
	v_add_u32_e32 v236, 0xfffff000, v254
	v_cmp_lt_i32_e32 vcc, 0xfff, v254
	v_lshrrev_b32_e32 v236, 10, v236
	v_lshlrev_b32_e32 v254, 12, v254
	v_add_u32_e32 v236, 1, v236
	v_cndmask_b32_e32 v236, 0, v236, vcc
	v_lshl_add_u64 v[226:227], v[254:255], 0, v[248:249]
	v_lshl_add_u64 v[230:231], v[254:255], 0, v[250:251]
	v_add_u32_e32 v236, s8, v236
	v_mad_i64_i32 v[234:235], s[0:1], v236, s33, v[252:253]
	global_load_dwordx4 v[154:157], v[224:225], off
	global_load_dwordx4 v[116:119], v[232:233], off
	global_load_dwordx4 v[158:161], v[224:225], off offset:64
	global_load_dwordx4 v[120:123], v[232:233], off offset:64
	global_load_dwordx4 v[162:165], v[224:225], off offset:128
	global_load_dwordx4 v[124:127], v[232:233], off offset:128
	global_load_dwordx4 v[166:169], v[224:225], off offset:192
	global_load_dwordx4 v[134:137], v[232:233], off offset:192
	global_load_dwordx4 v[208:211], v[226:227], off
	global_load_dwordx4 v[138:141], v[234:235], off
	global_load_dwordx4 v[212:215], v[226:227], off offset:64
	global_load_dwordx4 v[200:203], v[234:235], off offset:64
	global_load_dwordx4 v[216:219], v[226:227], off offset:128
	global_load_dwordx4 v[92:95], v[234:235], off offset:128
	global_load_dwordx4 v[220:223], v[226:227], off offset:192
	global_load_dwordx4 v[244:247], v[234:235], off offset:192
	s_waitcnt vmcnt(0)
	v_pk_mul_f32 v[28:29], v[28:29], v[116:117]
	v_pk_mul_f32 v[30:31], v[30:31], v[118:119]
	v_pk_fma_f32 v[28:29], v[154:155], s[6:7], v[28:29] op_sel_hi:[1,0,1]
	v_pk_fma_f32 v[30:31], v[156:157], s[6:7], v[30:31] op_sel_hi:[1,0,1]
	global_store_dwordx4 v[228:229], v[28:31], off
	v_pk_mul_f32 v[24:25], v[24:25], v[120:121]
	v_pk_mul_f32 v[26:27], v[26:27], v[122:123]
	v_pk_fma_f32 v[24:25], v[158:159], s[6:7], v[24:25] op_sel_hi:[1,0,1]
	v_pk_fma_f32 v[26:27], v[160:161], s[6:7], v[26:27] op_sel_hi:[1,0,1]
	global_store_dwordx4 v[228:229], v[24:27], off offset:64
	v_pk_mul_f32 v[20:21], v[20:21], v[124:125]
	v_pk_mul_f32 v[22:23], v[22:23], v[126:127]
	v_pk_fma_f32 v[20:21], v[162:163], s[6:7], v[20:21] op_sel_hi:[1,0,1]
	v_pk_fma_f32 v[22:23], v[164:165], s[6:7], v[22:23] op_sel_hi:[1,0,1]
	global_store_dwordx4 v[228:229], v[20:23], off offset:128
	v_pk_mul_f32 v[16:17], v[16:17], v[134:135]
	v_pk_mul_f32 v[18:19], v[18:19], v[136:137]
	v_pk_fma_f32 v[16:17], v[166:167], s[6:7], v[16:17] op_sel_hi:[1,0,1]
	v_pk_fma_f32 v[18:19], v[168:169], s[6:7], v[18:19] op_sel_hi:[1,0,1]
	global_store_dwordx4 v[228:229], v[16:19], off offset:192
	v_pk_mul_f32 v[12:13], v[12:13], v[138:139]
	v_pk_mul_f32 v[14:15], v[14:15], v[140:141]
	v_pk_fma_f32 v[12:13], v[208:209], s[6:7], v[12:13] op_sel_hi:[1,0,1]
	v_pk_fma_f32 v[14:15], v[210:211], s[6:7], v[14:15] op_sel_hi:[1,0,1]
	global_store_dwordx4 v[230:231], v[12:15], off
	v_pk_mul_f32 v[8:9], v[8:9], v[200:201]
	v_pk_mul_f32 v[10:11], v[10:11], v[202:203]
	v_pk_fma_f32 v[8:9], v[212:213], s[6:7], v[8:9] op_sel_hi:[1,0,1]
	v_pk_fma_f32 v[10:11], v[214:215], s[6:7], v[10:11] op_sel_hi:[1,0,1]
	global_store_dwordx4 v[230:231], v[8:11], off offset:64
	v_pk_mul_f32 v[4:5], v[4:5], v[92:93]
	v_pk_mul_f32 v[6:7], v[6:7], v[94:95]
	v_pk_fma_f32 v[4:5], v[216:217], s[6:7], v[4:5] op_sel_hi:[1,0,1]
	v_pk_fma_f32 v[6:7], v[218:219], s[6:7], v[6:7] op_sel_hi:[1,0,1]
	global_store_dwordx4 v[230:231], v[4:7], off offset:128
	v_pk_mul_f32 v[0:1], v[0:1], v[244:245]
	v_pk_mul_f32 v[2:3], v[2:3], v[246:247]
	v_pk_fma_f32 v[0:1], v[220:221], s[6:7], v[0:1] op_sel_hi:[1,0,1]
	v_pk_fma_f32 v[2:3], v[222:223], s[6:7], v[2:3] op_sel_hi:[1,0,1]
	global_store_dwordx4 v[230:231], v[0:3], off offset:192
	v_readlane_b32 s12, v242, 25
	v_readlane_b32 s13, v242, 26
	v_readlane_b32 s14, v242, 27
	v_readlane_b32 s15, v242, 28
	v_readlane_b32 s16, v242, 29
	v_readlane_b32 s17, v242, 30
	v_readlane_b32 s18, v242, 31
	v_readlane_b32 s19, v242, 32
	v_readlane_b32 s20, v242, 33
	v_readlane_b32 s21, v242, 34
	v_readlane_b32 s22, v242, 35
	v_readlane_b32 s23, v242, 36
	v_readlane_b32 s24, v242, 37
	v_readlane_b32 s25, v242, 38
	v_readlane_b32 s26, v242, 39
	v_readlane_b32 s27, v242, 40
	s_mov_b64 s[10:11], 0x2000
	s_movk_i32 s4, 0xfff
	s_waitcnt lgkmcnt(0)
	s_barrier
	s_cmpk_gt_i32 s9, 0xff
	s_cbranch_scc0 .LBB0_127

.LBB0_265:
	s_bitcmp1_b32 s9, 0
	s_cselect_b32 s9, 0x6000, 0
	v_lshl_add_u32 v46, v30, 2, s9
	v_lshl_add_u32 v47, v28, 2, s9
	s_andn2_b64 vcc, exec, s[12:13]
	ds_read_b128 v[72:75], v46 offset:256
	ds_read_b128 v[76:79], v46 offset:768
	ds_read_b128 v[84:87], v46 offset:1280
	ds_read2st64_b32 v[228:229], v47 offset0:2 offset1:8
	ds_read_b128 v[80:83], v46 offset:1024
	ds_read_b128 v[68:71], v46
	ds_read_b128 v[92:95], v46 offset:1792
	ds_read_b128 v[96:99], v46 offset:2304
	ds_read_b128 v[204:207], v46 offset:2816
	ds_read_b128 v[200:203], v46 offset:2560
	ds_read_b128 v[88:91], v46 offset:1536
	s_waitcnt lgkmcnt(5)
	v_pk_mul_f32 v[232:233], v[72:73], v[24:25]
	s_nop 0
	v_pk_fma_f32 v[232:233], v[74:75], v[26:27], v[232:233]
	s_nop 0
	v_add_f32_e32 v232, v232, v233
	ds_read_b128 v[212:215], v46 offset:3328
	ds_read_b128 v[216:219], v46 offset:3840
	ds_read_b128 v[224:227], v46 offset:4352
	ds_read2st64_b32 v[230:231], v47 offset0:14 offset1:20
	ds_read_b128 v[220:223], v46 offset:4096
	ds_read_b128 v[208:211], v46 offset:3072
	v_pk_mul_f32 v[50:51], v[228:229], v[84:85] op_sel_hi:[0,1]
	v_pk_mul_f32 v[52:53], v[228:229], v[86:87] op_sel_hi:[0,1]
	v_pk_fma_f32 v[50:51], v[76:77], v[24:25], v[50:51]
	v_pk_fma_f32 v[52:53], v[78:79], v[26:27], v[52:53]
	v_add_f32_dpp v232, v232, v232 quad_perm:[1,0,3,2] row_mask:0xf bank_mask:0xf bound_ctrl:1
	s_nop 1
	v_add_f32_dpp v232, v232, v232 quad_perm:[2,3,0,1] row_mask:0xf bank_mask:0xf bound_ctrl:1
	s_nop 1
	v_add_f32_dpp v232, v232, v232 row_half_mirror row_mask:0xf bank_mask:0xf bound_ctrl:1
	s_nop 1
	v_add_f32_dpp v232, v232, v232 row_mirror row_mask:0xf bank_mask:0xf bound_ctrl:1
	v_pk_fma_f32 v[24:25], v[80:81], v[232:233], v[50:51] op_sel_hi:[1,0,1] neg_lo:[1,0,0] neg_hi:[1,0,0]
	v_pk_fma_f32 v[26:27], v[82:83], v[232:233], v[52:53] op_sel_hi:[1,0,1] neg_lo:[1,0,0] neg_hi:[1,0,0]
	s_waitcnt lgkmcnt(6)
	v_pk_mul_f32 v[232:233], v[92:93], v[24:25]
	v_pk_mul_f32 v[234:235], v[68:69], v[24:25]
	v_pk_fma_f32 v[232:233], v[94:95], v[26:27], v[232:233]
	v_pk_fma_f32 v[234:235], v[70:71], v[26:27], v[234:235]
	v_add_f32_e32 v232, v232, v233
	v_add_f32_e32 v234, v234, v235
	ds_read_b128 v[72:75], v46 offset:4864
	ds_read_b128 v[76:79], v46 offset:5376
	ds_read_b128 v[84:87], v46 offset:5888
	ds_read_b128 v[80:83], v46 offset:5632
	ds_read_b128 v[68:71], v46 offset:4608
	v_pk_mul_f32 v[50:51], v[228:229], v[204:205] op_sel:[1,0] op_sel_hi:[1,1]
	v_pk_mul_f32 v[52:53], v[228:229], v[206:207] op_sel:[1,0] op_sel_hi:[1,1]
	v_pk_fma_f32 v[50:51], v[96:97], v[24:25], v[50:51]
	v_pk_fma_f32 v[52:53], v[98:99], v[26:27], v[52:53]
	v_add_f32_dpp v232, v232, v232 quad_perm:[1,0,3,2] row_mask:0xf bank_mask:0xf bound_ctrl:1
	v_add_f32_dpp v234, v234, v234 quad_perm:[1,0,3,2] row_mask:0xf bank_mask:0xf bound_ctrl:1
	s_nop 0
	v_add_f32_dpp v232, v232, v232 quad_perm:[2,3,0,1] row_mask:0xf bank_mask:0xf bound_ctrl:1
	v_add_f32_dpp v234, v234, v234 quad_perm:[2,3,0,1] row_mask:0xf bank_mask:0xf bound_ctrl:1
	v_cndmask_b32_e64 v54, 0, v234, s[42:43]
	v_add_f32_dpp v232, v232, v232 row_half_mirror row_mask:0xf bank_mask:0xf bound_ctrl:1
	s_nop 1
	v_add_f32_dpp v232, v232, v232 row_mirror row_mask:0xf bank_mask:0xf bound_ctrl:1
	v_pk_fma_f32 v[24:25], v[200:201], v[232:233], v[50:51] op_sel_hi:[1,0,1] neg_lo:[1,0,0] neg_hi:[1,0,0]
	v_pk_fma_f32 v[26:27], v[202:203], v[232:233], v[52:53] op_sel_hi:[1,0,1] neg_lo:[1,0,0] neg_hi:[1,0,0]
	s_waitcnt lgkmcnt(5)
	v_pk_mul_f32 v[232:233], v[212:213], v[24:25]
	v_pk_mul_f32 v[234:235], v[88:89], v[24:25]
	v_pk_fma_f32 v[232:233], v[214:215], v[26:27], v[232:233]
	v_pk_fma_f32 v[234:235], v[90:91], v[26:27], v[234:235]
	v_add_f32_e32 v232, v232, v233
	v_add_f32_e32 v234, v234, v235
	ds_read_b128 v[92:95], v46 offset:6400
	ds_read_b128 v[96:99], v46 offset:6912
	ds_read_b128 v[204:207], v46 offset:7424
	ds_read2st64_b32 v[228:229], v47 offset0:26 offset1:32
	ds_read_b128 v[200:203], v46 offset:7168
	ds_read_b128 v[88:91], v46 offset:6144
	v_pk_mul_f32 v[50:51], v[230:231], v[224:225] op_sel_hi:[0,1]
	v_pk_mul_f32 v[52:53], v[230:231], v[226:227] op_sel_hi:[0,1]
	v_pk_fma_f32 v[50:51], v[216:217], v[24:25], v[50:51]
	v_pk_fma_f32 v[52:53], v[218:219], v[26:27], v[52:53]
	v_add_f32_dpp v232, v232, v232 quad_perm:[1,0,3,2] row_mask:0xf bank_mask:0xf bound_ctrl:1
	v_add_f32_dpp v234, v234, v234 quad_perm:[1,0,3,2] row_mask:0xf bank_mask:0xf bound_ctrl:1
	s_nop 0
	v_add_f32_dpp v232, v232, v232 quad_perm:[2,3,0,1] row_mask:0xf bank_mask:0xf bound_ctrl:1
	v_add_f32_dpp v234, v234, v234 quad_perm:[2,3,0,1] row_mask:0xf bank_mask:0xf bound_ctrl:1
	v_cndmask_b32_e64 v54, v54, v234, s[44:45]
	v_add_f32_dpp v232, v232, v232 row_half_mirror row_mask:0xf bank_mask:0xf bound_ctrl:1
	s_nop 1
	v_add_f32_dpp v232, v232, v232 row_mirror row_mask:0xf bank_mask:0xf bound_ctrl:1
	v_pk_fma_f32 v[24:25], v[220:221], v[232:233], v[50:51] op_sel_hi:[1,0,1] neg_lo:[1,0,0] neg_hi:[1,0,0]
	v_pk_fma_f32 v[26:27], v[222:223], v[232:233], v[52:53] op_sel_hi:[1,0,1] neg_lo:[1,0,0] neg_hi:[1,0,0]
	s_waitcnt lgkmcnt(6)
	v_pk_mul_f32 v[232:233], v[72:73], v[24:25]
	v_pk_mul_f32 v[234:235], v[208:209], v[24:25]
	v_pk_fma_f32 v[232:233], v[74:75], v[26:27], v[232:233]
	v_pk_fma_f32 v[234:235], v[210:211], v[26:27], v[234:235]
	v_add_f32_e32 v232, v232, v233
	v_add_f32_e32 v234, v234, v235
	ds_read_b128 v[212:215], v46 offset:7936
	ds_read_b128 v[216:219], v46 offset:8448
	ds_read_b128 v[224:227], v46 offset:8960
	ds_read_b128 v[220:223], v46 offset:8704
	ds_read_b128 v[208:211], v46 offset:7680
	v_pk_mul_f32 v[50:51], v[230:231], v[84:85] op_sel:[1,0] op_sel_hi:[1,1]
	v_pk_mul_f32 v[52:53], v[230:231], v[86:87] op_sel:[1,0] op_sel_hi:[1,1]
	v_pk_fma_f32 v[50:51], v[76:77], v[24:25], v[50:51]
	v_pk_fma_f32 v[52:53], v[78:79], v[26:27], v[52:53]
	v_add_f32_dpp v232, v232, v232 quad_perm:[1,0,3,2] row_mask:0xf bank_mask:0xf bound_ctrl:1
	v_add_f32_dpp v234, v234, v234 quad_perm:[1,0,3,2] row_mask:0xf bank_mask:0xf bound_ctrl:1
	s_nop 0
	v_add_f32_dpp v232, v232, v232 quad_perm:[2,3,0,1] row_mask:0xf bank_mask:0xf bound_ctrl:1
	v_add_f32_dpp v234, v234, v234 quad_perm:[2,3,0,1] row_mask:0xf bank_mask:0xf bound_ctrl:1
	v_cndmask_b32_e64 v54, v54, v234, s[46:47]
	v_add_f32_dpp v232, v232, v232 row_half_mirror row_mask:0xf bank_mask:0xf bound_ctrl:1
	s_nop 1
	v_add_f32_dpp v232, v232, v232 row_mirror row_mask:0xf bank_mask:0xf bound_ctrl:1
	v_pk_fma_f32 v[24:25], v[80:81], v[232:233], v[50:51] op_sel_hi:[1,0,1] neg_lo:[1,0,0] neg_hi:[1,0,0]
	v_pk_fma_f32 v[26:27], v[82:83], v[232:233], v[52:53] op_sel_hi:[1,0,1] neg_lo:[1,0,0] neg_hi:[1,0,0]
	s_waitcnt lgkmcnt(5)
	v_pk_mul_f32 v[232:233], v[92:93], v[24:25]
	v_pk_mul_f32 v[234:235], v[68:69], v[24:25]
	v_pk_fma_f32 v[232:233], v[94:95], v[26:27], v[232:233]
	v_pk_fma_f32 v[234:235], v[70:71], v[26:27], v[234:235]
	v_add_f32_e32 v232, v232, v233
	v_add_f32_e32 v234, v234, v235
	ds_read_b128 v[72:75], v46 offset:9472
	ds_read_b128 v[76:79], v46 offset:9984
	ds_read_b128 v[84:87], v46 offset:10496
	ds_read2st64_b32 v[230:231], v47 offset0:38 offset1:44
	ds_read_b128 v[80:83], v46 offset:10240
	ds_read_b128 v[68:71], v46 offset:9216
	v_pk_mul_f32 v[50:51], v[228:229], v[204:205] op_sel_hi:[0,1]
	v_pk_mul_f32 v[52:53], v[228:229], v[206:207] op_sel_hi:[0,1]
	v_pk_fma_f32 v[50:51], v[96:97], v[24:25], v[50:51]
	v_pk_fma_f32 v[52:53], v[98:99], v[26:27], v[52:53]
	v_add_f32_dpp v232, v232, v232 quad_perm:[1,0,3,2] row_mask:0xf bank_mask:0xf bound_ctrl:1
	v_add_f32_dpp v234, v234, v234 quad_perm:[1,0,3,2] row_mask:0xf bank_mask:0xf bound_ctrl:1
	s_nop 0
	v_add_f32_dpp v232, v232, v232 quad_perm:[2,3,0,1] row_mask:0xf bank_mask:0xf bound_ctrl:1
	v_add_f32_dpp v234, v234, v234 quad_perm:[2,3,0,1] row_mask:0xf bank_mask:0xf bound_ctrl:1
	v_cndmask_b32_e64 v54, v54, v234, s[38:39]
	v_add_f32_dpp v232, v232, v232 row_half_mirror row_mask:0xf bank_mask:0xf bound_ctrl:1
	s_nop 1
	v_add_f32_dpp v232, v232, v232 row_mirror row_mask:0xf bank_mask:0xf bound_ctrl:1
	v_pk_fma_f32 v[24:25], v[200:201], v[232:233], v[50:51] op_sel_hi:[1,0,1] neg_lo:[1,0,0] neg_hi:[1,0,0]
	v_pk_fma_f32 v[26:27], v[202:203], v[232:233], v[52:53] op_sel_hi:[1,0,1] neg_lo:[1,0,0] neg_hi:[1,0,0]
	s_waitcnt lgkmcnt(6)
	v_pk_mul_f32 v[232:233], v[212:213], v[24:25]
	v_pk_mul_f32 v[234:235], v[88:89], v[24:25]
	v_pk_fma_f32 v[232:233], v[214:215], v[26:27], v[232:233]
	v_pk_fma_f32 v[234:235], v[90:91], v[26:27], v[234:235]
	v_add_f32_e32 v232, v232, v233
	v_add_f32_e32 v234, v234, v235
	ds_read_b128 v[92:95], v46 offset:11008
	ds_read_b128 v[96:99], v46 offset:11520
	ds_read_b128 v[204:207], v46 offset:12032
	ds_read_b128 v[200:203], v46 offset:11776
	ds_read_b128 v[88:91], v46 offset:10752
	v_pk_mul_f32 v[50:51], v[228:229], v[224:225] op_sel:[1,0] op_sel_hi:[1,1]
	v_pk_mul_f32 v[52:53], v[228:229], v[226:227] op_sel:[1,0] op_sel_hi:[1,1]
	v_pk_fma_f32 v[50:51], v[216:217], v[24:25], v[50:51]
	v_pk_fma_f32 v[52:53], v[218:219], v[26:27], v[52:53]
	v_add_f32_dpp v232, v232, v232 quad_perm:[1,0,3,2] row_mask:0xf bank_mask:0xf bound_ctrl:1
	v_add_f32_dpp v234, v234, v234 quad_perm:[1,0,3,2] row_mask:0xf bank_mask:0xf bound_ctrl:1
	s_nop 0
	v_add_f32_dpp v232, v232, v232 quad_perm:[2,3,0,1] row_mask:0xf bank_mask:0xf bound_ctrl:1
	v_add_f32_dpp v234, v234, v234 quad_perm:[2,3,0,1] row_mask:0xf bank_mask:0xf bound_ctrl:1
	v_cndmask_b32_e64 v55, 0, v234, s[42:43]
	v_add_f32_dpp v232, v232, v232 row_half_mirror row_mask:0xf bank_mask:0xf bound_ctrl:1
	s_nop 1
	v_add_f32_dpp v232, v232, v232 row_mirror row_mask:0xf bank_mask:0xf bound_ctrl:1
	v_pk_fma_f32 v[24:25], v[220:221], v[232:233], v[50:51] op_sel_hi:[1,0,1] neg_lo:[1,0,0] neg_hi:[1,0,0]
	v_pk_fma_f32 v[26:27], v[222:223], v[232:233], v[52:53] op_sel_hi:[1,0,1] neg_lo:[1,0,0] neg_hi:[1,0,0]
	s_waitcnt lgkmcnt(5)
	v_pk_mul_f32 v[232:233], v[72:73], v[24:25]
	v_pk_mul_f32 v[234:235], v[208:209], v[24:25]
	v_pk_fma_f32 v[232:233], v[74:75], v[26:27], v[232:233]
	v_pk_fma_f32 v[234:235], v[210:211], v[26:27], v[234:235]
	v_add_f32_e32 v232, v232, v233
	v_add_f32_e32 v234, v234, v235
	ds_read_b128 v[212:215], v46 offset:12544
	ds_read_b128 v[216:219], v46 offset:13056
	ds_read_b128 v[224:227], v46 offset:13568
	ds_read2st64_b32 v[228:229], v47 offset0:50 offset1:56
	ds_read_b128 v[220:223], v46 offset:13312
	ds_read_b128 v[208:211], v46 offset:12288
	v_pk_mul_f32 v[50:51], v[230:231], v[84:85] op_sel_hi:[0,1]
	v_pk_mul_f32 v[52:53], v[230:231], v[86:87] op_sel_hi:[0,1]
	v_pk_fma_f32 v[50:51], v[76:77], v[24:25], v[50:51]
	v_pk_fma_f32 v[52:53], v[78:79], v[26:27], v[52:53]
	v_add_f32_dpp v232, v232, v232 quad_perm:[1,0,3,2] row_mask:0xf bank_mask:0xf bound_ctrl:1
	v_add_f32_dpp v234, v234, v234 quad_perm:[1,0,3,2] row_mask:0xf bank_mask:0xf bound_ctrl:1
	s_nop 0
	v_add_f32_dpp v232, v232, v232 quad_perm:[2,3,0,1] row_mask:0xf bank_mask:0xf bound_ctrl:1
	v_add_f32_dpp v234, v234, v234 quad_perm:[2,3,0,1] row_mask:0xf bank_mask:0xf bound_ctrl:1
	v_cndmask_b32_e64 v55, v55, v234, s[44:45]
	v_add_f32_dpp v232, v232, v232 row_half_mirror row_mask:0xf bank_mask:0xf bound_ctrl:1
	s_nop 1
	v_add_f32_dpp v232, v232, v232 row_mirror row_mask:0xf bank_mask:0xf bound_ctrl:1
	v_pk_fma_f32 v[24:25], v[80:81], v[232:233], v[50:51] op_sel_hi:[1,0,1] neg_lo:[1,0,0] neg_hi:[1,0,0]
	v_pk_fma_f32 v[26:27], v[82:83], v[232:233], v[52:53] op_sel_hi:[1,0,1] neg_lo:[1,0,0] neg_hi:[1,0,0]
	s_waitcnt lgkmcnt(6)
	v_pk_mul_f32 v[232:233], v[92:93], v[24:25]
	v_pk_mul_f32 v[234:235], v[68:69], v[24:25]
	v_pk_fma_f32 v[232:233], v[94:95], v[26:27], v[232:233]
	v_pk_fma_f32 v[234:235], v[70:71], v[26:27], v[234:235]
	v_add_f32_e32 v232, v232, v233
	v_add_f32_e32 v234, v234, v235
	ds_read_b128 v[72:75], v46 offset:14080
	ds_read_b128 v[76:79], v46 offset:14592
	ds_read_b128 v[84:87], v46 offset:15104
	ds_read_b128 v[80:83], v46 offset:14848
	ds_read_b128 v[68:71], v46 offset:13824
	v_pk_mul_f32 v[50:51], v[230:231], v[204:205] op_sel:[1,0] op_sel_hi:[1,1]
	v_pk_mul_f32 v[52:53], v[230:231], v[206:207] op_sel:[1,0] op_sel_hi:[1,1]
	v_pk_fma_f32 v[50:51], v[96:97], v[24:25], v[50:51]
	v_pk_fma_f32 v[52:53], v[98:99], v[26:27], v[52:53]
	v_add_f32_dpp v232, v232, v232 quad_perm:[1,0,3,2] row_mask:0xf bank_mask:0xf bound_ctrl:1
	v_add_f32_dpp v234, v234, v234 quad_perm:[1,0,3,2] row_mask:0xf bank_mask:0xf bound_ctrl:1
	s_nop 0
	v_add_f32_dpp v232, v232, v232 quad_perm:[2,3,0,1] row_mask:0xf bank_mask:0xf bound_ctrl:1
	v_add_f32_dpp v234, v234, v234 quad_perm:[2,3,0,1] row_mask:0xf bank_mask:0xf bound_ctrl:1
	v_cndmask_b32_e64 v55, v55, v234, s[46:47]
	v_add_f32_dpp v232, v232, v232 row_half_mirror row_mask:0xf bank_mask:0xf bound_ctrl:1
	s_nop 1
	v_add_f32_dpp v232, v232, v232 row_mirror row_mask:0xf bank_mask:0xf bound_ctrl:1
	v_pk_fma_f32 v[24:25], v[200:201], v[232:233], v[50:51] op_sel_hi:[1,0,1] neg_lo:[1,0,0] neg_hi:[1,0,0]
	v_pk_fma_f32 v[26:27], v[202:203], v[232:233], v[52:53] op_sel_hi:[1,0,1] neg_lo:[1,0,0] neg_hi:[1,0,0]
	s_waitcnt lgkmcnt(5)
	v_pk_mul_f32 v[232:233], v[212:213], v[24:25]
	v_pk_mul_f32 v[234:235], v[88:89], v[24:25]
	v_pk_fma_f32 v[232:233], v[214:215], v[26:27], v[232:233]
	v_pk_fma_f32 v[234:235], v[90:91], v[26:27], v[234:235]
	v_add_f32_e32 v232, v232, v233
	v_add_f32_e32 v234, v234, v235
	ds_read_b128 v[92:95], v46 offset:15616
	ds_read_b128 v[96:99], v46 offset:16128
	ds_read_b128 v[204:207], v46 offset:16640
	ds_read2st64_b32 v[230:231], v47 offset0:62 offset1:68
	ds_read_b128 v[200:203], v46 offset:16384
	ds_read_b128 v[88:91], v46 offset:15360
	v_pk_mul_f32 v[50:51], v[228:229], v[224:225] op_sel_hi:[0,1]
	v_pk_mul_f32 v[52:53], v[228:229], v[226:227] op_sel_hi:[0,1]
	v_pk_fma_f32 v[50:51], v[216:217], v[24:25], v[50:51]
	v_pk_fma_f32 v[52:53], v[218:219], v[26:27], v[52:53]
	v_add_f32_dpp v232, v232, v232 quad_perm:[1,0,3,2] row_mask:0xf bank_mask:0xf bound_ctrl:1
	v_add_f32_dpp v234, v234, v234 quad_perm:[1,0,3,2] row_mask:0xf bank_mask:0xf bound_ctrl:1
	s_nop 0
	v_add_f32_dpp v232, v232, v232 quad_perm:[2,3,0,1] row_mask:0xf bank_mask:0xf bound_ctrl:1
	v_add_f32_dpp v234, v234, v234 quad_perm:[2,3,0,1] row_mask:0xf bank_mask:0xf bound_ctrl:1
	v_cndmask_b32_e64 v55, v55, v234, s[38:39]
	v_add_f32_dpp v232, v232, v232 row_half_mirror row_mask:0xf bank_mask:0xf bound_ctrl:1
	s_nop 1
	v_add_f32_dpp v232, v232, v232 row_mirror row_mask:0xf bank_mask:0xf bound_ctrl:1
	v_pk_fma_f32 v[24:25], v[220:221], v[232:233], v[50:51] op_sel_hi:[1,0,1] neg_lo:[1,0,0] neg_hi:[1,0,0]
	v_pk_fma_f32 v[26:27], v[222:223], v[232:233], v[52:53] op_sel_hi:[1,0,1] neg_lo:[1,0,0] neg_hi:[1,0,0]
	s_waitcnt lgkmcnt(6)
	v_pk_mul_f32 v[232:233], v[72:73], v[24:25]
	v_pk_mul_f32 v[234:235], v[208:209], v[24:25]
	v_pk_fma_f32 v[232:233], v[74:75], v[26:27], v[232:233]
	v_pk_fma_f32 v[234:235], v[210:211], v[26:27], v[234:235]
	v_add_f32_e32 v232, v232, v233
	v_add_f32_e32 v234, v234, v235
	ds_read_b128 v[212:215], v46 offset:17152
	ds_read_b128 v[216:219], v46 offset:17664
	ds_read_b128 v[224:227], v46 offset:18176
	ds_read_b128 v[220:223], v46 offset:17920
	ds_read_b128 v[208:211], v46 offset:16896
	v_pk_mul_f32 v[50:51], v[228:229], v[84:85] op_sel:[1,0] op_sel_hi:[1,1]
	v_pk_mul_f32 v[52:53], v[228:229], v[86:87] op_sel:[1,0] op_sel_hi:[1,1]
	v_pk_fma_f32 v[50:51], v[76:77], v[24:25], v[50:51]
	v_pk_fma_f32 v[52:53], v[78:79], v[26:27], v[52:53]
	v_add_f32_dpp v232, v232, v232 quad_perm:[1,0,3,2] row_mask:0xf bank_mask:0xf bound_ctrl:1
	v_add_f32_dpp v234, v234, v234 quad_perm:[1,0,3,2] row_mask:0xf bank_mask:0xf bound_ctrl:1
	s_nop 0
	v_add_f32_dpp v232, v232, v232 quad_perm:[2,3,0,1] row_mask:0xf bank_mask:0xf bound_ctrl:1
	v_add_f32_dpp v234, v234, v234 quad_perm:[2,3,0,1] row_mask:0xf bank_mask:0xf bound_ctrl:1
	v_cndmask_b32_e64 v56, 0, v234, s[42:43]
	v_add_f32_dpp v232, v232, v232 row_half_mirror row_mask:0xf bank_mask:0xf bound_ctrl:1
	v_add_f32_dpp v54, v54, v54 row_ror:8 row_mask:0xf bank_mask:0xf bound_ctrl:1
	v_add_f32_dpp v55, v55, v55 row_ror:8 row_mask:0xf bank_mask:0xf bound_ctrl:1
	v_add_f32_dpp v232, v232, v232 row_mirror row_mask:0xf bank_mask:0xf bound_ctrl:1
	v_pk_fma_f32 v[24:25], v[80:81], v[232:233], v[50:51] op_sel_hi:[1,0,1] neg_lo:[1,0,0] neg_hi:[1,0,0]
	v_pk_fma_f32 v[26:27], v[82:83], v[232:233], v[52:53] op_sel_hi:[1,0,1] neg_lo:[1,0,0] neg_hi:[1,0,0]
	s_waitcnt lgkmcnt(5)
	v_pk_mul_f32 v[232:233], v[92:93], v[24:25]
	v_pk_mul_f32 v[234:235], v[68:69], v[24:25]
	v_pk_fma_f32 v[232:233], v[94:95], v[26:27], v[232:233]
	v_pk_fma_f32 v[234:235], v[70:71], v[26:27], v[234:235]
	v_add_f32_e32 v232, v232, v233
	v_add_f32_e32 v234, v234, v235
	ds_read_b128 v[72:75], v46 offset:18688
	ds_read_b128 v[76:79], v46 offset:19200
	ds_read_b128 v[84:87], v46 offset:19712
	ds_read2st64_b32 v[228:229], v47 offset0:74 offset1:80
	ds_read_b128 v[80:83], v46 offset:19456
	ds_read_b128 v[68:71], v46 offset:18432
	v_pk_mul_f32 v[50:51], v[230:231], v[204:205] op_sel_hi:[0,1]
	v_pk_mul_f32 v[52:53], v[230:231], v[206:207] op_sel_hi:[0,1]
	v_pk_fma_f32 v[50:51], v[96:97], v[24:25], v[50:51]
	v_pk_fma_f32 v[52:53], v[98:99], v[26:27], v[52:53]
	v_add_f32_dpp v232, v232, v232 quad_perm:[1,0,3,2] row_mask:0xf bank_mask:0xf bound_ctrl:1
	v_add_f32_dpp v234, v234, v234 quad_perm:[1,0,3,2] row_mask:0xf bank_mask:0xf bound_ctrl:1
	s_nop 0
	v_add_f32_dpp v232, v232, v232 quad_perm:[2,3,0,1] row_mask:0xf bank_mask:0xf bound_ctrl:1
	v_add_f32_dpp v234, v234, v234 quad_perm:[2,3,0,1] row_mask:0xf bank_mask:0xf bound_ctrl:1
	v_cndmask_b32_e64 v56, v56, v234, s[44:45]
	v_add_f32_dpp v232, v232, v232 row_half_mirror row_mask:0xf bank_mask:0xf bound_ctrl:1
	s_nop 0
	v_add_f32_dpp v54, v54, v54 row_ror:4 row_mask:0xf bank_mask:0xf bound_ctrl:1
	v_add_f32_dpp v232, v232, v232 row_mirror row_mask:0xf bank_mask:0xf bound_ctrl:1
	v_pk_fma_f32 v[24:25], v[200:201], v[232:233], v[50:51] op_sel_hi:[1,0,1] neg_lo:[1,0,0] neg_hi:[1,0,0]
	v_pk_fma_f32 v[26:27], v[202:203], v[232:233], v[52:53] op_sel_hi:[1,0,1] neg_lo:[1,0,0] neg_hi:[1,0,0]
	s_waitcnt lgkmcnt(6)
	v_pk_mul_f32 v[232:233], v[212:213], v[24:25]
	v_pk_mul_f32 v[234:235], v[88:89], v[24:25]
	v_pk_fma_f32 v[232:233], v[214:215], v[26:27], v[232:233]
	v_pk_fma_f32 v[234:235], v[90:91], v[26:27], v[234:235]
	v_add_f32_e32 v232, v232, v233
	v_add_f32_e32 v234, v234, v235
	ds_read_b128 v[92:95], v46 offset:20224
	ds_read_b128 v[96:99], v46 offset:20736
	ds_read_b128 v[204:207], v46 offset:21248
	ds_read_b128 v[200:203], v46 offset:20992
	ds_read_b128 v[88:91], v46 offset:19968
	v_pk_mul_f32 v[50:51], v[230:231], v[224:225] op_sel:[1,0] op_sel_hi:[1,1]
	v_pk_mul_f32 v[52:53], v[230:231], v[226:227] op_sel:[1,0] op_sel_hi:[1,1]
	v_pk_fma_f32 v[50:51], v[216:217], v[24:25], v[50:51]
	v_pk_fma_f32 v[52:53], v[218:219], v[26:27], v[52:53]
	v_add_f32_dpp v232, v232, v232 quad_perm:[1,0,3,2] row_mask:0xf bank_mask:0xf bound_ctrl:1
	v_add_f32_dpp v234, v234, v234 quad_perm:[1,0,3,2] row_mask:0xf bank_mask:0xf bound_ctrl:1
	s_nop 0
	v_add_f32_dpp v232, v232, v232 quad_perm:[2,3,0,1] row_mask:0xf bank_mask:0xf bound_ctrl:1
	v_add_f32_dpp v234, v234, v234 quad_perm:[2,3,0,1] row_mask:0xf bank_mask:0xf bound_ctrl:1
	v_cndmask_b32_e64 v56, v56, v234, s[46:47]
	v_add_f32_dpp v232, v232, v232 row_half_mirror row_mask:0xf bank_mask:0xf bound_ctrl:1
	v_add_f32_dpp v55, v55, v55 row_ror:4 row_mask:0xf bank_mask:0xf bound_ctrl:1
	v_cndmask_b32_e64 v49, v55, v54, s[40:41]
	v_add_f32_dpp v232, v232, v232 row_mirror row_mask:0xf bank_mask:0xf bound_ctrl:1
	v_pk_fma_f32 v[24:25], v[220:221], v[232:233], v[50:51] op_sel_hi:[1,0,1] neg_lo:[1,0,0] neg_hi:[1,0,0]
	v_pk_fma_f32 v[26:27], v[222:223], v[232:233], v[52:53] op_sel_hi:[1,0,1] neg_lo:[1,0,0] neg_hi:[1,0,0]
	s_waitcnt lgkmcnt(5)
	v_pk_mul_f32 v[232:233], v[72:73], v[24:25]
	v_pk_mul_f32 v[234:235], v[208:209], v[24:25]
	v_pk_fma_f32 v[232:233], v[74:75], v[26:27], v[232:233]
	v_pk_fma_f32 v[234:235], v[210:211], v[26:27], v[234:235]
	v_add_f32_e32 v232, v232, v233
	v_add_f32_e32 v234, v234, v235
	ds_read_b128 v[212:215], v46 offset:21760
	ds_read_b128 v[216:219], v46 offset:22272
	ds_read_b128 v[224:227], v46 offset:22784
	ds_read2st64_b32 v[230:231], v47 offset0:86 offset1:92
	ds_read_b128 v[220:223], v46 offset:22528
	ds_read_b128 v[208:211], v46 offset:21504
	v_pk_mul_f32 v[50:51], v[228:229], v[84:85] op_sel_hi:[0,1]
	v_pk_mul_f32 v[52:53], v[228:229], v[86:87] op_sel_hi:[0,1]
	v_pk_fma_f32 v[50:51], v[76:77], v[24:25], v[50:51]
	v_pk_fma_f32 v[52:53], v[78:79], v[26:27], v[52:53]
	v_add_f32_dpp v232, v232, v232 quad_perm:[1,0,3,2] row_mask:0xf bank_mask:0xf bound_ctrl:1
	v_add_f32_dpp v234, v234, v234 quad_perm:[1,0,3,2] row_mask:0xf bank_mask:0xf bound_ctrl:1
	s_nop 0
	v_add_f32_dpp v232, v232, v232 quad_perm:[2,3,0,1] row_mask:0xf bank_mask:0xf bound_ctrl:1
	v_add_f32_dpp v234, v234, v234 quad_perm:[2,3,0,1] row_mask:0xf bank_mask:0xf bound_ctrl:1
	v_cndmask_b32_e64 v56, v56, v234, s[38:39]
	v_add_f32_dpp v232, v232, v232 row_half_mirror row_mask:0xf bank_mask:0xf bound_ctrl:1
	v_cndmask_b32_e64 v48, 0, v49, s[48:49]
	s_nop 0
	v_add_f32_dpp v232, v232, v232 row_mirror row_mask:0xf bank_mask:0xf bound_ctrl:1
	v_pk_fma_f32 v[24:25], v[80:81], v[232:233], v[50:51] op_sel_hi:[1,0,1] neg_lo:[1,0,0] neg_hi:[1,0,0]
	v_pk_fma_f32 v[26:27], v[82:83], v[232:233], v[52:53] op_sel_hi:[1,0,1] neg_lo:[1,0,0] neg_hi:[1,0,0]
	s_waitcnt lgkmcnt(6)
	v_pk_mul_f32 v[232:233], v[92:93], v[24:25]
	v_pk_mul_f32 v[234:235], v[68:69], v[24:25]
	v_pk_fma_f32 v[232:233], v[94:95], v[26:27], v[232:233]
	v_pk_fma_f32 v[234:235], v[70:71], v[26:27], v[234:235]
	v_add_f32_e32 v232, v232, v233
	v_add_f32_e32 v234, v234, v235
	ds_read_b128 v[72:75], v46 offset:23296
	ds_read_b128 v[76:79], v46 offset:23808
	ds_read_b128 v[84:87], v46 offset:24320
	ds_read_b128 v[80:83], v46 offset:24064
	ds_read_b128 v[68:71], v46 offset:23040
	v_pk_mul_f32 v[50:51], v[228:229], v[204:205] op_sel:[1,0] op_sel_hi:[1,1]
	v_pk_mul_f32 v[52:53], v[228:229], v[206:207] op_sel:[1,0] op_sel_hi:[1,1]
	v_pk_fma_f32 v[50:51], v[96:97], v[24:25], v[50:51]
	v_pk_fma_f32 v[52:53], v[98:99], v[26:27], v[52:53]
	v_add_f32_dpp v232, v232, v232 quad_perm:[1,0,3,2] row_mask:0xf bank_mask:0xf bound_ctrl:1
	v_add_f32_dpp v234, v234, v234 quad_perm:[1,0,3,2] row_mask:0xf bank_mask:0xf bound_ctrl:1
	s_nop 0
	v_add_f32_dpp v232, v232, v232 quad_perm:[2,3,0,1] row_mask:0xf bank_mask:0xf bound_ctrl:1
	v_add_f32_dpp v234, v234, v234 quad_perm:[2,3,0,1] row_mask:0xf bank_mask:0xf bound_ctrl:1
	v_cndmask_b32_e64 v57, 0, v234, s[42:43]
	v_add_f32_dpp v232, v232, v232 row_half_mirror row_mask:0xf bank_mask:0xf bound_ctrl:1
	s_nop 1
	v_add_f32_dpp v232, v232, v232 row_mirror row_mask:0xf bank_mask:0xf bound_ctrl:1
	v_pk_fma_f32 v[24:25], v[200:201], v[232:233], v[50:51] op_sel_hi:[1,0,1] neg_lo:[1,0,0] neg_hi:[1,0,0]
	v_pk_fma_f32 v[26:27], v[202:203], v[232:233], v[52:53] op_sel_hi:[1,0,1] neg_lo:[1,0,0] neg_hi:[1,0,0]
	s_waitcnt lgkmcnt(5)
	v_pk_mul_f32 v[232:233], v[212:213], v[24:25]
	v_pk_mul_f32 v[234:235], v[88:89], v[24:25]
	v_pk_fma_f32 v[232:233], v[214:215], v[26:27], v[232:233]
	v_pk_fma_f32 v[234:235], v[90:91], v[26:27], v[234:235]
	v_add_f32_e32 v232, v232, v233
	v_add_f32_e32 v234, v234, v235
	v_pk_mul_f32 v[50:51], v[230:231], v[224:225] op_sel_hi:[0,1]
	v_pk_mul_f32 v[52:53], v[230:231], v[226:227] op_sel_hi:[0,1]
	v_pk_fma_f32 v[50:51], v[216:217], v[24:25], v[50:51]
	v_pk_fma_f32 v[52:53], v[218:219], v[26:27], v[52:53]
	v_add_f32_dpp v232, v232, v232 quad_perm:[1,0,3,2] row_mask:0xf bank_mask:0xf bound_ctrl:1
	v_add_f32_dpp v234, v234, v234 quad_perm:[1,0,3,2] row_mask:0xf bank_mask:0xf bound_ctrl:1
	s_nop 0
	v_add_f32_dpp v232, v232, v232 quad_perm:[2,3,0,1] row_mask:0xf bank_mask:0xf bound_ctrl:1
	v_add_f32_dpp v234, v234, v234 quad_perm:[2,3,0,1] row_mask:0xf bank_mask:0xf bound_ctrl:1
	v_cndmask_b32_e64 v57, v57, v234, s[44:45]
	v_add_f32_dpp v232, v232, v232 row_half_mirror row_mask:0xf bank_mask:0xf bound_ctrl:1
	s_nop 1
	v_add_f32_dpp v232, v232, v232 row_mirror row_mask:0xf bank_mask:0xf bound_ctrl:1
	v_pk_fma_f32 v[24:25], v[220:221], v[232:233], v[50:51] op_sel_hi:[1,0,1] neg_lo:[1,0,0] neg_hi:[1,0,0]
	v_pk_fma_f32 v[26:27], v[222:223], v[232:233], v[52:53] op_sel_hi:[1,0,1] neg_lo:[1,0,0] neg_hi:[1,0,0]
	s_waitcnt lgkmcnt(0)
	v_pk_mul_f32 v[232:233], v[72:73], v[24:25]
	v_pk_mul_f32 v[234:235], v[208:209], v[24:25]
	v_pk_fma_f32 v[232:233], v[74:75], v[26:27], v[232:233]
	v_pk_fma_f32 v[234:235], v[210:211], v[26:27], v[234:235]
	v_add_f32_e32 v232, v232, v233
	v_add_f32_e32 v234, v234, v235
	v_pk_mul_f32 v[50:51], v[230:231], v[84:85] op_sel:[1,0] op_sel_hi:[1,1]
	v_pk_mul_f32 v[52:53], v[230:231], v[86:87] op_sel:[1,0] op_sel_hi:[1,1]
	v_pk_fma_f32 v[50:51], v[76:77], v[24:25], v[50:51]
	v_pk_fma_f32 v[52:53], v[78:79], v[26:27], v[52:53]
	v_add_f32_dpp v232, v232, v232 quad_perm:[1,0,3,2] row_mask:0xf bank_mask:0xf bound_ctrl:1
	v_add_f32_dpp v234, v234, v234 quad_perm:[1,0,3,2] row_mask:0xf bank_mask:0xf bound_ctrl:1
	s_nop 0
	v_add_f32_dpp v232, v232, v232 quad_perm:[2,3,0,1] row_mask:0xf bank_mask:0xf bound_ctrl:1
	v_add_f32_dpp v234, v234, v234 quad_perm:[2,3,0,1] row_mask:0xf bank_mask:0xf bound_ctrl:1
	v_cndmask_b32_e64 v57, v57, v234, s[46:47]
	v_add_f32_dpp v232, v232, v232 row_half_mirror row_mask:0xf bank_mask:0xf bound_ctrl:1
	s_nop 1
	v_add_f32_dpp v232, v232, v232 row_mirror row_mask:0xf bank_mask:0xf bound_ctrl:1
	v_pk_fma_f32 v[24:25], v[80:81], v[232:233], v[50:51] op_sel_hi:[1,0,1] neg_lo:[1,0,0] neg_hi:[1,0,0]
	v_pk_fma_f32 v[26:27], v[82:83], v[232:233], v[52:53] op_sel_hi:[1,0,1] neg_lo:[1,0,0] neg_hi:[1,0,0]
	v_pk_mul_f32 v[234:235], v[68:69], v[24:25]
	s_nop 0
	v_pk_fma_f32 v[234:235], v[70:71], v[26:27], v[234:235]
	s_nop 0
	v_add_f32_e32 v234, v234, v235
	s_nop 1
	v_add_f32_dpp v234, v234, v234 quad_perm:[1,0,3,2] row_mask:0xf bank_mask:0xf bound_ctrl:1
	s_nop 1
	v_add_f32_dpp v234, v234, v234 quad_perm:[2,3,0,1] row_mask:0xf bank_mask:0xf bound_ctrl:1
	v_cndmask_b32_e64 v57, v57, v234, s[38:39]
	v_add_f32_dpp v56, v56, v56 row_ror:8 row_mask:0xf bank_mask:0xf bound_ctrl:1
	s_nop 0
	v_add_f32_dpp v57, v57, v57 row_ror:8 row_mask:0xf bank_mask:0xf bound_ctrl:1
	s_nop 0
	v_add_f32_dpp v56, v56, v56 row_ror:4 row_mask:0xf bank_mask:0xf bound_ctrl:1
	v_add_f32_dpp v57, v57, v57 row_ror:4 row_mask:0xf bank_mask:0xf bound_ctrl:1
	v_cndmask_b32_e64 v49, v57, v56, s[40:41]
	v_cndmask_b32_e64 v48, v49, v48, s[48:49]
	v_cndmask_b32_e64 v46, v64, v31, s[36:37]
	v_add_u32_e32 v46, s0, v46
	v_ashrrev_i32_e32 v47, 31, v46
	v_lshlrev_b64 v[46:47], 10, v[46:47]
	v_lshl_add_u64 v[46:47], v[32:33], 0, v[46:47]
	global_store_dword v[46:47], v48, off
	s_cbranch_vccnz .LBB0_267
	s_bitcmp1_b32 s5, 0
	s_cselect_b32 s9, 0x6000, 0
	v_lshl_add_u32 v46, v58, 2, s9
	s_waitcnt vmcnt(6)
	ds_write_b128 v46, v[0:3]
	v_lshl_add_u32 v46, v59, 2, s9
	s_waitcnt vmcnt(5)
	ds_write_b128 v46, v[4:7]
	v_lshl_add_u32 v46, v60, 2, s9
	s_waitcnt vmcnt(4)
	ds_write_b128 v46, v[8:11]
	v_lshl_add_u32 v46, v61, 2, s9
	s_waitcnt vmcnt(3)
	ds_write_b128 v46, v[12:15]
	v_lshl_add_u32 v46, v62, 2, s9
	s_waitcnt vmcnt(2)
	ds_write_b128 v46, v[16:19]
	v_lshl_add_u32 v46, v63, 2, s9
	s_waitcnt vmcnt(1)
	ds_write_b128 v46, v[20:23]

	.amdhsa_kernel _Z10fwd_kernel6Paramsiii
		.amdhsa_group_segment_fixed_size 73744
		.amdhsa_private_segment_fixed_size 0
		.amdhsa_kernarg_size 872
		.amdhsa_user_sgpr_count 2
		.amdhsa_user_sgpr_dispatch_ptr 0
		.amdhsa_user_sgpr_queue_ptr 0
		.amdhsa_user_sgpr_kernarg_segment_ptr 1
		.amdhsa_user_sgpr_dispatch_id 0
		.amdhsa_user_sgpr_kernarg_preload_length 0
		.amdhsa_user_sgpr_kernarg_preload_offset 0
		.amdhsa_user_sgpr_private_segment_size 0
		.amdhsa_uses_dynamic_stack 0
		.amdhsa_enable_private_segment 0
		.amdhsa_system_sgpr_workgroup_id_x 1
		.amdhsa_system_sgpr_workgroup_id_y 0
		.amdhsa_system_sgpr_workgroup_id_z 0
		.amdhsa_system_sgpr_workgroup_info 0
		.amdhsa_system_vgpr_workitem_id 2
		.amdhsa_next_free_vgpr 256
		.amdhsa_next_free_sgpr 100
		.amdhsa_accum_offset 256
		.amdhsa_reserve_vcc 1
		.amdhsa_float_round_mode_32 0
		.amdhsa_float_round_mode_16_64 0
		.amdhsa_float_denorm_mode_32 3
		.amdhsa_float_denorm_mode_16_64 3
		.amdhsa_dx10_clamp 1
		.amdhsa_ieee_mode 1
		.amdhsa_fp16_overflow 0
		.amdhsa_tg_split 0
		.amdhsa_exception_fp_ieee_invalid_op 0
		.amdhsa_exception_fp_denorm_src 0
		.amdhsa_exception_fp_ieee_div_zero 0
		.amdhsa_exception_fp_ieee_overflow 0
		.amdhsa_exception_fp_ieee_underflow 0
		.amdhsa_exception_fp_ieee_inexact 0
		.amdhsa_exception_int_div_zero 0
	.end_amdhsa_kernel

amdhsa.kernels:
  - .agpr_count:     0
    .args:
      - .offset:         0
        .size:           600
        .value_kind:     by_value
      - .offset:         600
        .size:           4
        .value_kind:     by_value
      - .offset:         604
        .size:           4
        .value_kind:     by_value
      - .offset:         608
        .size:           4
        .value_kind:     by_value
      - .offset:         616
        .size:           4
        .value_kind:     hidden_block_count_x
      - .offset:         620
        .size:           4
        .value_kind:     hidden_block_count_y
      - .offset:         624
        .size:           4
        .value_kind:     hidden_block_count_z
      - .offset:         628
        .size:           2
        .value_kind:     hidden_group_size_x
      - .offset:         630
        .size:           2
        .value_kind:     hidden_group_size_y
      - .offset:         632
        .size:           2
        .value_kind:     hidden_group_size_z
      - .offset:         634
        .size:           2
        .value_kind:     hidden_remainder_x
      - .offset:         636
        .size:           2
        .value_kind:     hidden_remainder_y
      - .offset:         638
        .size:           2
        .value_kind:     hidden_remainder_z
      - .offset:         656
        .size:           8
        .value_kind:     hidden_global_offset_x
      - .offset:         664
        .size:           8
        .value_kind:     hidden_global_offset_y
      - .offset:         672
        .size:           8
        .value_kind:     hidden_global_offset_z
      - .offset:         680
        .size:           2
        .value_kind:     hidden_grid_dims
      - .offset:         704
        .size:           8
        .value_kind:     hidden_multigrid_sync_arg
    .group_segment_fixed_size: 73744
    .kernarg_segment_align: 8
    .kernarg_segment_size: 872
    .language:       OpenCL C
    .language_version:
      - 2
      - 0
    .max_flat_workgroup_size: 256
    .name:           _Z10fwd_kernel6Paramsiii
    .private_segment_fixed_size: 0
    .sgpr_count:     106
    .sgpr_spill_count: 468
    .symbol:         _Z10fwd_kernel6Paramsiii.kd
    .uniform_work_group_size: 1
    .uses_dynamic_stack: false
    .vgpr_count:     256
    .vgpr_spill_count: 0
    .wavefront_size: 64
